# decay epilogue: log1p via hardware log with the u/((1+u)-1) correction instead of the libm expansion, bias loaded once per tile
# speedup vs baseline: 1.0320x; 1.0166x over previous
.LBB0_401:
	s_and_b64 vcc, exec, s[2:3]
	s_cbranch_vccz .LBB0_406
	s_cmp_gt_i32 s4, 5
	s_mov_b64 s[2:3], -1
	s_cbranch_scc0 .LBB0_404
	v_lshl_add_u32 v142, s44, 8, v29
	v_lshl_or_b32 v144, s63, 8, v179
	v_ashrrev_i32_e32 v145, 31, v144
	v_lshlrev_b64 v[144:145], 2, v[144:145]
	v_lshl_add_u64 v[174:175], v[132:133], 0, v[144:145]
	global_load_dwordx4 v[210:213], v[174:175], off
	global_load_dwordx4 v[214:217], v[174:175], off offset:64
	global_load_dwordx4 v[218:221], v[174:175], off offset:512
	global_load_dwordx4 v[222:225], v[174:175], off offset:576
	v_mad_i64_i32 v[180:181], s[2:3], v164, v142, 0
	v_lshl_add_u64 v[180:181], v[180:181], 2, v[130:131]
	v_lshl_add_u64 v[180:181], v[180:181], 0, v[144:145]
	v_or_b32_e32 v143, 16, v142
	v_mad_i64_i32 v[182:183], s[2:3], v164, v143, 0
	v_lshl_add_u64 v[182:183], v[182:183], 2, v[130:131]
	v_lshl_add_u64 v[182:183], v[182:183], 0, v[144:145]
	v_or_b32_e32 v143, 32, v142
	v_mad_i64_i32 v[184:185], s[2:3], v164, v143, 0
	v_lshl_add_u64 v[184:185], v[184:185], 2, v[130:131]
	v_lshl_add_u64 v[184:185], v[184:185], 0, v[144:145]
	v_or_b32_e32 v143, 48, v142
	v_mad_i64_i32 v[186:187], s[2:3], v164, v143, 0
	v_lshl_add_u64 v[186:187], v[186:187], 2, v[130:131]
	v_lshl_add_u64 v[186:187], v[186:187], 0, v[144:145]
	v_or_b32_e32 v143, 0x80, v142
	v_mad_i64_i32 v[188:189], s[2:3], v164, v143, 0
	v_lshl_add_u64 v[188:189], v[188:189], 2, v[130:131]
	v_lshl_add_u64 v[188:189], v[188:189], 0, v[144:145]
	v_or_b32_e32 v143, 0x90, v142
	v_mad_i64_i32 v[190:191], s[2:3], v164, v143, 0
	v_lshl_add_u64 v[190:191], v[190:191], 2, v[130:131]
	v_lshl_add_u64 v[190:191], v[190:191], 0, v[144:145]
	v_or_b32_e32 v143, 0xa0, v142
	v_mad_i64_i32 v[192:193], s[2:3], v164, v143, 0
	v_lshl_add_u64 v[192:193], v[192:193], 2, v[130:131]
	v_lshl_add_u64 v[192:193], v[192:193], 0, v[144:145]
	v_or_b32_e32 v143, 0xb0, v142
	v_mad_i64_i32 v[194:195], s[2:3], v164, v143, 0
	v_lshl_add_u64 v[194:195], v[194:195], 2, v[130:131]
	v_lshl_add_u64 v[194:195], v[194:195], 0, v[144:145]
	s_waitcnt vmcnt(0)
	v_add_f32_e32 v226, v114, v210
	v_add_f32_e32 v227, v115, v211
	v_add_f32_e32 v228, v116, v212
	v_add_f32_e32 v229, v117, v213
	v_mul_f32_e64 v134, |v226|, s86
	v_mul_f32_e64 v135, |v227|, s86
	v_mul_f32_e64 v136, |v228|, s86
	v_mul_f32_e64 v137, |v229|, s86
	v_exp_f32_e32 v134, v134
	v_exp_f32_e32 v135, v135
	v_exp_f32_e32 v136, v136
	v_exp_f32_e32 v137, v137
	v_max_f32_e64 v169, -v226, 0
	v_max_f32_e64 v170, -v227, 0
	v_max_f32_e64 v171, -v228, 0
	v_max_f32_e64 v172, -v229, 0
	v_add_f32_e32 v138, 1.0, v134
	v_add_f32_e32 v139, 1.0, v135
	v_add_f32_e32 v140, 1.0, v136
	v_add_f32_e32 v141, 1.0, v137
	v_add_f32_e32 v165, -1.0, v138
	v_add_f32_e32 v166, -1.0, v139
	v_add_f32_e32 v167, -1.0, v140
	v_add_f32_e32 v168, -1.0, v141
	v_log_f32_e32 v138, v138
	v_log_f32_e32 v139, v139
	v_log_f32_e32 v140, v140
	v_log_f32_e32 v141, v141
	v_max_f32_e32 v165, 0x0da24260, v165
	v_max_f32_e32 v166, 0x0da24260, v166
	v_max_f32_e32 v167, 0x0da24260, v167
	v_max_f32_e32 v168, 0x0da24260, v168
	v_rcp_f32_e32 v165, v165
	v_rcp_f32_e32 v166, v166
	v_rcp_f32_e32 v167, v167
	v_rcp_f32_e32 v168, v168
	v_mul_f32_e32 v165, v134, v165
	v_mul_f32_e32 v166, v135, v166
	v_mul_f32_e32 v167, v136, v167
	v_mul_f32_e32 v168, v137, v168
	v_mul_f32_e32 v138, v138, v165
	v_mul_f32_e32 v139, v139, v166
	v_mul_f32_e32 v140, v140, v167
	v_mul_f32_e32 v141, v141, v168
	v_fmamk_f32 v169, v138, 0x3f317218, v169
	v_fmamk_f32 v170, v139, 0x3f317218, v170
	v_fmamk_f32 v171, v140, 0x3f317218, v171
	v_fmamk_f32 v172, v141, 0x3f317218, v172
	v_sub_f32_e32 v169, -0.5, v169
	v_sub_f32_e32 v170, -0.5, v170
	v_sub_f32_e32 v171, -0.5, v171
	v_sub_f32_e32 v172, -0.5, v172
	v_mul_f32_e32 v169, 0x3fb8aa3b, v169
	v_mul_f32_e32 v170, 0x3fb8aa3b, v170
	v_mul_f32_e32 v171, 0x3fb8aa3b, v171
	v_mul_f32_e32 v172, 0x3fb8aa3b, v172
	v_exp_f32_e32 v169, v169
	v_exp_f32_e32 v170, v170
	v_exp_f32_e32 v171, v171
	v_exp_f32_e32 v172, v172
	v_mul_f32_e32 v169, 0xbfb8aa3b, v169
	v_mul_f32_e32 v170, 0xbfb8aa3b, v170
	v_mul_f32_e32 v171, 0xbfb8aa3b, v171
	v_mul_f32_e32 v172, 0xbfb8aa3b, v172
	v_exp_f32_e32 v226, v169
	v_exp_f32_e32 v227, v170
	v_exp_f32_e32 v228, v171
	v_exp_f32_e32 v229, v172
	global_store_dwordx4 v[180:181], v[226:229], off
	v_add_f32_e32 v230, v126, v214
	v_add_f32_e32 v231, v127, v215
	v_add_f32_e32 v232, v128, v216
	v_add_f32_e32 v233, v129, v217
	v_mul_f32_e64 v134, |v230|, s86
	v_mul_f32_e64 v135, |v231|, s86
	v_mul_f32_e64 v136, |v232|, s86
	v_mul_f32_e64 v137, |v233|, s86
	v_exp_f32_e32 v134, v134
	v_exp_f32_e32 v135, v135
	v_exp_f32_e32 v136, v136
	v_exp_f32_e32 v137, v137
	v_max_f32_e64 v169, -v230, 0
	v_max_f32_e64 v170, -v231, 0
	v_max_f32_e64 v171, -v232, 0
	v_max_f32_e64 v172, -v233, 0
	v_add_f32_e32 v138, 1.0, v134
	v_add_f32_e32 v139, 1.0, v135
	v_add_f32_e32 v140, 1.0, v136
	v_add_f32_e32 v141, 1.0, v137
	v_add_f32_e32 v165, -1.0, v138
	v_add_f32_e32 v166, -1.0, v139
	v_add_f32_e32 v167, -1.0, v140
	v_add_f32_e32 v168, -1.0, v141
	v_log_f32_e32 v138, v138
	v_log_f32_e32 v139, v139
	v_log_f32_e32 v140, v140
	v_log_f32_e32 v141, v141
	v_max_f32_e32 v165, 0x0da24260, v165
	v_max_f32_e32 v166, 0x0da24260, v166
	v_max_f32_e32 v167, 0x0da24260, v167
	v_max_f32_e32 v168, 0x0da24260, v168
	v_rcp_f32_e32 v165, v165
	v_rcp_f32_e32 v166, v166
	v_rcp_f32_e32 v167, v167
	v_rcp_f32_e32 v168, v168
	v_mul_f32_e32 v165, v134, v165
	v_mul_f32_e32 v166, v135, v166
	v_mul_f32_e32 v167, v136, v167
	v_mul_f32_e32 v168, v137, v168
	v_mul_f32_e32 v138, v138, v165
	v_mul_f32_e32 v139, v139, v166
	v_mul_f32_e32 v140, v140, v167
	v_mul_f32_e32 v141, v141, v168
	v_fmamk_f32 v169, v138, 0x3f317218, v169
	v_fmamk_f32 v170, v139, 0x3f317218, v170
	v_fmamk_f32 v171, v140, 0x3f317218, v171
	v_fmamk_f32 v172, v141, 0x3f317218, v172
	v_sub_f32_e32 v169, -0.5, v169
	v_sub_f32_e32 v170, -0.5, v170
	v_sub_f32_e32 v171, -0.5, v171
	v_sub_f32_e32 v172, -0.5, v172
	v_mul_f32_e32 v169, 0x3fb8aa3b, v169
	v_mul_f32_e32 v170, 0x3fb8aa3b, v170
	v_mul_f32_e32 v171, 0x3fb8aa3b, v171
	v_mul_f32_e32 v172, 0x3fb8aa3b, v172
	v_exp_f32_e32 v169, v169
	v_exp_f32_e32 v170, v170
	v_exp_f32_e32 v171, v171
	v_exp_f32_e32 v172, v172
	v_mul_f32_e32 v169, 0xbfb8aa3b, v169
	v_mul_f32_e32 v170, 0xbfb8aa3b, v170
	v_mul_f32_e32 v171, 0xbfb8aa3b, v171
	v_mul_f32_e32 v172, 0xbfb8aa3b, v172
	v_exp_f32_e32 v230, v169
	v_exp_f32_e32 v231, v170
	v_exp_f32_e32 v232, v171
	v_exp_f32_e32 v233, v172
	global_store_dwordx4 v[180:181], v[230:233], off offset:64
	v_add_f32_e32 v226, v122, v218
	v_add_f32_e32 v227, v123, v219
	v_add_f32_e32 v228, v124, v220
	v_add_f32_e32 v229, v125, v221
	v_mul_f32_e64 v134, |v226|, s86
	v_mul_f32_e64 v135, |v227|, s86
	v_mul_f32_e64 v136, |v228|, s86
	v_mul_f32_e64 v137, |v229|, s86
	v_exp_f32_e32 v134, v134
	v_exp_f32_e32 v135, v135
	v_exp_f32_e32 v136, v136
	v_exp_f32_e32 v137, v137
	v_max_f32_e64 v169, -v226, 0
	v_max_f32_e64 v170, -v227, 0
	v_max_f32_e64 v171, -v228, 0
	v_max_f32_e64 v172, -v229, 0
	v_add_f32_e32 v138, 1.0, v134
	v_add_f32_e32 v139, 1.0, v135
	v_add_f32_e32 v140, 1.0, v136
	v_add_f32_e32 v141, 1.0, v137
	v_add_f32_e32 v165, -1.0, v138
	v_add_f32_e32 v166, -1.0, v139
	v_add_f32_e32 v167, -1.0, v140
	v_add_f32_e32 v168, -1.0, v141
	v_log_f32_e32 v138, v138
	v_log_f32_e32 v139, v139
	v_log_f32_e32 v140, v140
	v_log_f32_e32 v141, v141
	v_max_f32_e32 v165, 0x0da24260, v165
	v_max_f32_e32 v166, 0x0da24260, v166
	v_max_f32_e32 v167, 0x0da24260, v167
	v_max_f32_e32 v168, 0x0da24260, v168
	v_rcp_f32_e32 v165, v165
	v_rcp_f32_e32 v166, v166
	v_rcp_f32_e32 v167, v167
	v_rcp_f32_e32 v168, v168
	v_mul_f32_e32 v165, v134, v165
	v_mul_f32_e32 v166, v135, v166
	v_mul_f32_e32 v167, v136, v167
	v_mul_f32_e32 v168, v137, v168
	v_mul_f32_e32 v138, v138, v165
	v_mul_f32_e32 v139, v139, v166
	v_mul_f32_e32 v140, v140, v167
	v_mul_f32_e32 v141, v141, v168
	v_fmamk_f32 v169, v138, 0x3f317218, v169
	v_fmamk_f32 v170, v139, 0x3f317218, v170
	v_fmamk_f32 v171, v140, 0x3f317218, v171
	v_fmamk_f32 v172, v141, 0x3f317218, v172
	v_sub_f32_e32 v169, -0.5, v169
	v_sub_f32_e32 v170, -0.5, v170
	v_sub_f32_e32 v171, -0.5, v171
	v_sub_f32_e32 v172, -0.5, v172
	v_mul_f32_e32 v169, 0x3fb8aa3b, v169
	v_mul_f32_e32 v170, 0x3fb8aa3b, v170
	v_mul_f32_e32 v171, 0x3fb8aa3b, v171
	v_mul_f32_e32 v172, 0x3fb8aa3b, v172
	v_exp_f32_e32 v169, v169
	v_exp_f32_e32 v170, v170
	v_exp_f32_e32 v171, v171
	v_exp_f32_e32 v172, v172
	v_mul_f32_e32 v169, 0xbfb8aa3b, v169
	v_mul_f32_e32 v170, 0xbfb8aa3b, v170
	v_mul_f32_e32 v171, 0xbfb8aa3b, v171
	v_mul_f32_e32 v172, 0xbfb8aa3b, v172
	v_exp_f32_e32 v226, v169
	v_exp_f32_e32 v227, v170
	v_exp_f32_e32 v228, v171
	v_exp_f32_e32 v229, v172
	global_store_dwordx4 v[180:181], v[226:229], off offset:512
	v_add_f32_e32 v230, v118, v222
	v_add_f32_e32 v231, v119, v223
	v_add_f32_e32 v232, v120, v224
	v_add_f32_e32 v233, v121, v225
	v_mul_f32_e64 v134, |v230|, s86
	v_mul_f32_e64 v135, |v231|, s86
	v_mul_f32_e64 v136, |v232|, s86
	v_mul_f32_e64 v137, |v233|, s86
	v_exp_f32_e32 v134, v134
	v_exp_f32_e32 v135, v135
	v_exp_f32_e32 v136, v136
	v_exp_f32_e32 v137, v137
	v_max_f32_e64 v169, -v230, 0
	v_max_f32_e64 v170, -v231, 0
	v_max_f32_e64 v171, -v232, 0
	v_max_f32_e64 v172, -v233, 0
	v_add_f32_e32 v138, 1.0, v134
	v_add_f32_e32 v139, 1.0, v135
	v_add_f32_e32 v140, 1.0, v136
	v_add_f32_e32 v141, 1.0, v137
	v_add_f32_e32 v165, -1.0, v138
	v_add_f32_e32 v166, -1.0, v139
	v_add_f32_e32 v167, -1.0, v140
	v_add_f32_e32 v168, -1.0, v141
	v_log_f32_e32 v138, v138
	v_log_f32_e32 v139, v139
	v_log_f32_e32 v140, v140
	v_log_f32_e32 v141, v141
	v_max_f32_e32 v165, 0x0da24260, v165
	v_max_f32_e32 v166, 0x0da24260, v166
	v_max_f32_e32 v167, 0x0da24260, v167
	v_max_f32_e32 v168, 0x0da24260, v168
	v_rcp_f32_e32 v165, v165
	v_rcp_f32_e32 v166, v166
	v_rcp_f32_e32 v167, v167
	v_rcp_f32_e32 v168, v168
	v_mul_f32_e32 v165, v134, v165
	v_mul_f32_e32 v166, v135, v166
	v_mul_f32_e32 v167, v136, v167
	v_mul_f32_e32 v168, v137, v168
	v_mul_f32_e32 v138, v138, v165
	v_mul_f32_e32 v139, v139, v166
	v_mul_f32_e32 v140, v140, v167
	v_mul_f32_e32 v141, v141, v168
	v_fmamk_f32 v169, v138, 0x3f317218, v169
	v_fmamk_f32 v170, v139, 0x3f317218, v170
	v_fmamk_f32 v171, v140, 0x3f317218, v171
	v_fmamk_f32 v172, v141, 0x3f317218, v172
	v_sub_f32_e32 v169, -0.5, v169
	v_sub_f32_e32 v170, -0.5, v170
	v_sub_f32_e32 v171, -0.5, v171
	v_sub_f32_e32 v172, -0.5, v172
	v_mul_f32_e32 v169, 0x3fb8aa3b, v169
	v_mul_f32_e32 v170, 0x3fb8aa3b, v170
	v_mul_f32_e32 v171, 0x3fb8aa3b, v171
	v_mul_f32_e32 v172, 0x3fb8aa3b, v172
	v_exp_f32_e32 v169, v169
	v_exp_f32_e32 v170, v170
	v_exp_f32_e32 v171, v171
	v_exp_f32_e32 v172, v172
	v_mul_f32_e32 v169, 0xbfb8aa3b, v169
	v_mul_f32_e32 v170, 0xbfb8aa3b, v170
	v_mul_f32_e32 v171, 0xbfb8aa3b, v171
	v_mul_f32_e32 v172, 0xbfb8aa3b, v172
	v_exp_f32_e32 v230, v169
	v_exp_f32_e32 v231, v170
	v_exp_f32_e32 v232, v171
	v_exp_f32_e32 v233, v172
	global_store_dwordx4 v[180:181], v[230:233], off offset:576
	v_add_f32_e32 v226, v110, v210
	v_add_f32_e32 v227, v111, v211
	v_add_f32_e32 v228, v112, v212
	v_add_f32_e32 v229, v113, v213
	v_mul_f32_e64 v134, |v226|, s86
	v_mul_f32_e64 v135, |v227|, s86
	v_mul_f32_e64 v136, |v228|, s86
	v_mul_f32_e64 v137, |v229|, s86
	v_exp_f32_e32 v134, v134
	v_exp_f32_e32 v135, v135
	v_exp_f32_e32 v136, v136
	v_exp_f32_e32 v137, v137
	v_max_f32_e64 v169, -v226, 0
	v_max_f32_e64 v170, -v227, 0
	v_max_f32_e64 v171, -v228, 0
	v_max_f32_e64 v172, -v229, 0
	v_add_f32_e32 v138, 1.0, v134
	v_add_f32_e32 v139, 1.0, v135
	v_add_f32_e32 v140, 1.0, v136
	v_add_f32_e32 v141, 1.0, v137
	v_add_f32_e32 v165, -1.0, v138
	v_add_f32_e32 v166, -1.0, v139
	v_add_f32_e32 v167, -1.0, v140
	v_add_f32_e32 v168, -1.0, v141
	v_log_f32_e32 v138, v138
	v_log_f32_e32 v139, v139
	v_log_f32_e32 v140, v140
	v_log_f32_e32 v141, v141
	v_max_f32_e32 v165, 0x0da24260, v165
	v_max_f32_e32 v166, 0x0da24260, v166
	v_max_f32_e32 v167, 0x0da24260, v167
	v_max_f32_e32 v168, 0x0da24260, v168
	v_rcp_f32_e32 v165, v165
	v_rcp_f32_e32 v166, v166
	v_rcp_f32_e32 v167, v167
	v_rcp_f32_e32 v168, v168
	v_mul_f32_e32 v165, v134, v165
	v_mul_f32_e32 v166, v135, v166
	v_mul_f32_e32 v167, v136, v167
	v_mul_f32_e32 v168, v137, v168
	v_mul_f32_e32 v138, v138, v165
	v_mul_f32_e32 v139, v139, v166
	v_mul_f32_e32 v140, v140, v167
	v_mul_f32_e32 v141, v141, v168
	v_fmamk_f32 v169, v138, 0x3f317218, v169
	v_fmamk_f32 v170, v139, 0x3f317218, v170
	v_fmamk_f32 v171, v140, 0x3f317218, v171
	v_fmamk_f32 v172, v141, 0x3f317218, v172
	v_sub_f32_e32 v169, -0.5, v169
	v_sub_f32_e32 v170, -0.5, v170
	v_sub_f32_e32 v171, -0.5, v171
	v_sub_f32_e32 v172, -0.5, v172
	v_mul_f32_e32 v169, 0x3fb8aa3b, v169
	v_mul_f32_e32 v170, 0x3fb8aa3b, v170
	v_mul_f32_e32 v171, 0x3fb8aa3b, v171
	v_mul_f32_e32 v172, 0x3fb8aa3b, v172
	v_exp_f32_e32 v169, v169
	v_exp_f32_e32 v170, v170
	v_exp_f32_e32 v171, v171
	v_exp_f32_e32 v172, v172
	v_mul_f32_e32 v169, 0xbfb8aa3b, v169
	v_mul_f32_e32 v170, 0xbfb8aa3b, v170
	v_mul_f32_e32 v171, 0xbfb8aa3b, v171
	v_mul_f32_e32 v172, 0xbfb8aa3b, v172
	v_exp_f32_e32 v226, v169
	v_exp_f32_e32 v227, v170
	v_exp_f32_e32 v228, v171
	v_exp_f32_e32 v229, v172
	global_store_dwordx4 v[182:183], v[226:229], off
	v_add_f32_e32 v230, v106, v214
	v_add_f32_e32 v231, v107, v215
	v_add_f32_e32 v232, v108, v216
	v_add_f32_e32 v233, v109, v217
	v_mul_f32_e64 v134, |v230|, s86
	v_mul_f32_e64 v135, |v231|, s86
	v_mul_f32_e64 v136, |v232|, s86
	v_mul_f32_e64 v137, |v233|, s86
	v_exp_f32_e32 v134, v134
	v_exp_f32_e32 v135, v135
	v_exp_f32_e32 v136, v136
	v_exp_f32_e32 v137, v137
	v_max_f32_e64 v169, -v230, 0
	v_max_f32_e64 v170, -v231, 0
	v_max_f32_e64 v171, -v232, 0
	v_max_f32_e64 v172, -v233, 0
	v_add_f32_e32 v138, 1.0, v134
	v_add_f32_e32 v139, 1.0, v135
	v_add_f32_e32 v140, 1.0, v136
	v_add_f32_e32 v141, 1.0, v137
	v_add_f32_e32 v165, -1.0, v138
	v_add_f32_e32 v166, -1.0, v139
	v_add_f32_e32 v167, -1.0, v140
	v_add_f32_e32 v168, -1.0, v141
	v_log_f32_e32 v138, v138
	v_log_f32_e32 v139, v139
	v_log_f32_e32 v140, v140
	v_log_f32_e32 v141, v141
	v_max_f32_e32 v165, 0x0da24260, v165
	v_max_f32_e32 v166, 0x0da24260, v166
	v_max_f32_e32 v167, 0x0da24260, v167
	v_max_f32_e32 v168, 0x0da24260, v168
	v_rcp_f32_e32 v165, v165
	v_rcp_f32_e32 v166, v166
	v_rcp_f32_e32 v167, v167
	v_rcp_f32_e32 v168, v168
	v_mul_f32_e32 v165, v134, v165
	v_mul_f32_e32 v166, v135, v166
	v_mul_f32_e32 v167, v136, v167
	v_mul_f32_e32 v168, v137, v168
	v_mul_f32_e32 v138, v138, v165
	v_mul_f32_e32 v139, v139, v166
	v_mul_f32_e32 v140, v140, v167
	v_mul_f32_e32 v141, v141, v168
	v_fmamk_f32 v169, v138, 0x3f317218, v169
	v_fmamk_f32 v170, v139, 0x3f317218, v170
	v_fmamk_f32 v171, v140, 0x3f317218, v171
	v_fmamk_f32 v172, v141, 0x3f317218, v172
	v_sub_f32_e32 v169, -0.5, v169
	v_sub_f32_e32 v170, -0.5, v170
	v_sub_f32_e32 v171, -0.5, v171
	v_sub_f32_e32 v172, -0.5, v172
	v_mul_f32_e32 v169, 0x3fb8aa3b, v169
	v_mul_f32_e32 v170, 0x3fb8aa3b, v170
	v_mul_f32_e32 v171, 0x3fb8aa3b, v171
	v_mul_f32_e32 v172, 0x3fb8aa3b, v172
	v_exp_f32_e32 v169, v169
	v_exp_f32_e32 v170, v170
	v_exp_f32_e32 v171, v171
	v_exp_f32_e32 v172, v172
	v_mul_f32_e32 v169, 0xbfb8aa3b, v169
	v_mul_f32_e32 v170, 0xbfb8aa3b, v170
	v_mul_f32_e32 v171, 0xbfb8aa3b, v171
	v_mul_f32_e32 v172, 0xbfb8aa3b, v172
	v_exp_f32_e32 v230, v169
	v_exp_f32_e32 v231, v170
	v_exp_f32_e32 v232, v171
	v_exp_f32_e32 v233, v172
	global_store_dwordx4 v[182:183], v[230:233], off offset:64
	v_add_f32_e32 v226, v102, v218
	v_add_f32_e32 v227, v103, v219
	v_add_f32_e32 v228, v104, v220
	v_add_f32_e32 v229, v105, v221
	v_mul_f32_e64 v134, |v226|, s86
	v_mul_f32_e64 v135, |v227|, s86
	v_mul_f32_e64 v136, |v228|, s86
	v_mul_f32_e64 v137, |v229|, s86
	v_exp_f32_e32 v134, v134
	v_exp_f32_e32 v135, v135
	v_exp_f32_e32 v136, v136
	v_exp_f32_e32 v137, v137
	v_max_f32_e64 v169, -v226, 0
	v_max_f32_e64 v170, -v227, 0
	v_max_f32_e64 v171, -v228, 0
	v_max_f32_e64 v172, -v229, 0
	v_add_f32_e32 v138, 1.0, v134
	v_add_f32_e32 v139, 1.0, v135
	v_add_f32_e32 v140, 1.0, v136
	v_add_f32_e32 v141, 1.0, v137
	v_add_f32_e32 v165, -1.0, v138
	v_add_f32_e32 v166, -1.0, v139
	v_add_f32_e32 v167, -1.0, v140
	v_add_f32_e32 v168, -1.0, v141
	v_log_f32_e32 v138, v138
	v_log_f32_e32 v139, v139
	v_log_f32_e32 v140, v140
	v_log_f32_e32 v141, v141
	v_max_f32_e32 v165, 0x0da24260, v165
	v_max_f32_e32 v166, 0x0da24260, v166
	v_max_f32_e32 v167, 0x0da24260, v167
	v_max_f32_e32 v168, 0x0da24260, v168
	v_rcp_f32_e32 v165, v165
	v_rcp_f32_e32 v166, v166
	v_rcp_f32_e32 v167, v167
	v_rcp_f32_e32 v168, v168
	v_mul_f32_e32 v165, v134, v165
	v_mul_f32_e32 v166, v135, v166
	v_mul_f32_e32 v167, v136, v167
	v_mul_f32_e32 v168, v137, v168
	v_mul_f32_e32 v138, v138, v165
	v_mul_f32_e32 v139, v139, v166
	v_mul_f32_e32 v140, v140, v167
	v_mul_f32_e32 v141, v141, v168
	v_fmamk_f32 v169, v138, 0x3f317218, v169
	v_fmamk_f32 v170, v139, 0x3f317218, v170
	v_fmamk_f32 v171, v140, 0x3f317218, v171
	v_fmamk_f32 v172, v141, 0x3f317218, v172
	v_sub_f32_e32 v169, -0.5, v169
	v_sub_f32_e32 v170, -0.5, v170
	v_sub_f32_e32 v171, -0.5, v171
	v_sub_f32_e32 v172, -0.5, v172
	v_mul_f32_e32 v169, 0x3fb8aa3b, v169
	v_mul_f32_e32 v170, 0x3fb8aa3b, v170
	v_mul_f32_e32 v171, 0x3fb8aa3b, v171
	v_mul_f32_e32 v172, 0x3fb8aa3b, v172
	v_exp_f32_e32 v169, v169
	v_exp_f32_e32 v170, v170
	v_exp_f32_e32 v171, v171
	v_exp_f32_e32 v172, v172
	v_mul_f32_e32 v169, 0xbfb8aa3b, v169
	v_mul_f32_e32 v170, 0xbfb8aa3b, v170
	v_mul_f32_e32 v171, 0xbfb8aa3b, v171
	v_mul_f32_e32 v172, 0xbfb8aa3b, v172
	v_exp_f32_e32 v226, v169
	v_exp_f32_e32 v227, v170
	v_exp_f32_e32 v228, v171
	v_exp_f32_e32 v229, v172
	global_store_dwordx4 v[182:183], v[226:229], off offset:512
	v_add_f32_e32 v230, v98, v222
	v_add_f32_e32 v231, v99, v223
	v_add_f32_e32 v232, v100, v224
	v_add_f32_e32 v233, v101, v225
	v_mul_f32_e64 v134, |v230|, s86
	v_mul_f32_e64 v135, |v231|, s86
	v_mul_f32_e64 v136, |v232|, s86
	v_mul_f32_e64 v137, |v233|, s86
	v_exp_f32_e32 v134, v134
	v_exp_f32_e32 v135, v135
	v_exp_f32_e32 v136, v136
	v_exp_f32_e32 v137, v137
	v_max_f32_e64 v169, -v230, 0
	v_max_f32_e64 v170, -v231, 0
	v_max_f32_e64 v171, -v232, 0
	v_max_f32_e64 v172, -v233, 0
	v_add_f32_e32 v138, 1.0, v134
	v_add_f32_e32 v139, 1.0, v135
	v_add_f32_e32 v140, 1.0, v136
	v_add_f32_e32 v141, 1.0, v137
	v_add_f32_e32 v165, -1.0, v138
	v_add_f32_e32 v166, -1.0, v139
	v_add_f32_e32 v167, -1.0, v140
	v_add_f32_e32 v168, -1.0, v141
	v_log_f32_e32 v138, v138
	v_log_f32_e32 v139, v139
	v_log_f32_e32 v140, v140
	v_log_f32_e32 v141, v141
	v_max_f32_e32 v165, 0x0da24260, v165
	v_max_f32_e32 v166, 0x0da24260, v166
	v_max_f32_e32 v167, 0x0da24260, v167
	v_max_f32_e32 v168, 0x0da24260, v168
	v_rcp_f32_e32 v165, v165
	v_rcp_f32_e32 v166, v166
	v_rcp_f32_e32 v167, v167
	v_rcp_f32_e32 v168, v168
	v_mul_f32_e32 v165, v134, v165
	v_mul_f32_e32 v166, v135, v166
	v_mul_f32_e32 v167, v136, v167
	v_mul_f32_e32 v168, v137, v168
	v_mul_f32_e32 v138, v138, v165
	v_mul_f32_e32 v139, v139, v166
	v_mul_f32_e32 v140, v140, v167
	v_mul_f32_e32 v141, v141, v168
	v_fmamk_f32 v169, v138, 0x3f317218, v169
	v_fmamk_f32 v170, v139, 0x3f317218, v170
	v_fmamk_f32 v171, v140, 0x3f317218, v171
	v_fmamk_f32 v172, v141, 0x3f317218, v172
	v_sub_f32_e32 v169, -0.5, v169
	v_sub_f32_e32 v170, -0.5, v170
	v_sub_f32_e32 v171, -0.5, v171
	v_sub_f32_e32 v172, -0.5, v172
	v_mul_f32_e32 v169, 0x3fb8aa3b, v169
	v_mul_f32_e32 v170, 0x3fb8aa3b, v170
	v_mul_f32_e32 v171, 0x3fb8aa3b, v171
	v_mul_f32_e32 v172, 0x3fb8aa3b, v172
	v_exp_f32_e32 v169, v169
	v_exp_f32_e32 v170, v170
	v_exp_f32_e32 v171, v171
	v_exp_f32_e32 v172, v172
	v_mul_f32_e32 v169, 0xbfb8aa3b, v169
	v_mul_f32_e32 v170, 0xbfb8aa3b, v170
	v_mul_f32_e32 v171, 0xbfb8aa3b, v171
	v_mul_f32_e32 v172, 0xbfb8aa3b, v172
	v_exp_f32_e32 v230, v169
	v_exp_f32_e32 v231, v170
	v_exp_f32_e32 v232, v171
	v_exp_f32_e32 v233, v172
	global_store_dwordx4 v[182:183], v[230:233], off offset:576
	v_add_f32_e32 v226, v94, v210
	v_add_f32_e32 v227, v95, v211
	v_add_f32_e32 v228, v96, v212
	v_add_f32_e32 v229, v97, v213
	v_mul_f32_e64 v134, |v226|, s86
	v_mul_f32_e64 v135, |v227|, s86
	v_mul_f32_e64 v136, |v228|, s86
	v_mul_f32_e64 v137, |v229|, s86
	v_exp_f32_e32 v134, v134
	v_exp_f32_e32 v135, v135
	v_exp_f32_e32 v136, v136
	v_exp_f32_e32 v137, v137
	v_max_f32_e64 v169, -v226, 0
	v_max_f32_e64 v170, -v227, 0
	v_max_f32_e64 v171, -v228, 0
	v_max_f32_e64 v172, -v229, 0
	v_add_f32_e32 v138, 1.0, v134
	v_add_f32_e32 v139, 1.0, v135
	v_add_f32_e32 v140, 1.0, v136
	v_add_f32_e32 v141, 1.0, v137
	v_add_f32_e32 v165, -1.0, v138
	v_add_f32_e32 v166, -1.0, v139
	v_add_f32_e32 v167, -1.0, v140
	v_add_f32_e32 v168, -1.0, v141
	v_log_f32_e32 v138, v138
	v_log_f32_e32 v139, v139
	v_log_f32_e32 v140, v140
	v_log_f32_e32 v141, v141
	v_max_f32_e32 v165, 0x0da24260, v165
	v_max_f32_e32 v166, 0x0da24260, v166
	v_max_f32_e32 v167, 0x0da24260, v167
	v_max_f32_e32 v168, 0x0da24260, v168
	v_rcp_f32_e32 v165, v165
	v_rcp_f32_e32 v166, v166
	v_rcp_f32_e32 v167, v167
	v_rcp_f32_e32 v168, v168
	v_mul_f32_e32 v165, v134, v165
	v_mul_f32_e32 v166, v135, v166
	v_mul_f32_e32 v167, v136, v167
	v_mul_f32_e32 v168, v137, v168
	v_mul_f32_e32 v138, v138, v165
	v_mul_f32_e32 v139, v139, v166
	v_mul_f32_e32 v140, v140, v167
	v_mul_f32_e32 v141, v141, v168
	v_fmamk_f32 v169, v138, 0x3f317218, v169
	v_fmamk_f32 v170, v139, 0x3f317218, v170
	v_fmamk_f32 v171, v140, 0x3f317218, v171
	v_fmamk_f32 v172, v141, 0x3f317218, v172
	v_sub_f32_e32 v169, -0.5, v169
	v_sub_f32_e32 v170, -0.5, v170
	v_sub_f32_e32 v171, -0.5, v171
	v_sub_f32_e32 v172, -0.5, v172
	v_mul_f32_e32 v169, 0x3fb8aa3b, v169
	v_mul_f32_e32 v170, 0x3fb8aa3b, v170
	v_mul_f32_e32 v171, 0x3fb8aa3b, v171
	v_mul_f32_e32 v172, 0x3fb8aa3b, v172
	v_exp_f32_e32 v169, v169
	v_exp_f32_e32 v170, v170
	v_exp_f32_e32 v171, v171
	v_exp_f32_e32 v172, v172
	v_mul_f32_e32 v169, 0xbfb8aa3b, v169
	v_mul_f32_e32 v170, 0xbfb8aa3b, v170
	v_mul_f32_e32 v171, 0xbfb8aa3b, v171
	v_mul_f32_e32 v172, 0xbfb8aa3b, v172
	v_exp_f32_e32 v226, v169
	v_exp_f32_e32 v227, v170
	v_exp_f32_e32 v228, v171
	v_exp_f32_e32 v229, v172
	global_store_dwordx4 v[184:185], v[226:229], off
	v_add_f32_e32 v230, v90, v214
	v_add_f32_e32 v231, v91, v215
	v_add_f32_e32 v232, v92, v216
	v_add_f32_e32 v233, v93, v217
	v_mul_f32_e64 v134, |v230|, s86
	v_mul_f32_e64 v135, |v231|, s86
	v_mul_f32_e64 v136, |v232|, s86
	v_mul_f32_e64 v137, |v233|, s86
	v_exp_f32_e32 v134, v134
	v_exp_f32_e32 v135, v135
	v_exp_f32_e32 v136, v136
	v_exp_f32_e32 v137, v137
	v_max_f32_e64 v169, -v230, 0
	v_max_f32_e64 v170, -v231, 0
	v_max_f32_e64 v171, -v232, 0
	v_max_f32_e64 v172, -v233, 0
	v_add_f32_e32 v138, 1.0, v134
	v_add_f32_e32 v139, 1.0, v135
	v_add_f32_e32 v140, 1.0, v136
	v_add_f32_e32 v141, 1.0, v137
	v_add_f32_e32 v165, -1.0, v138
	v_add_f32_e32 v166, -1.0, v139
	v_add_f32_e32 v167, -1.0, v140
	v_add_f32_e32 v168, -1.0, v141
	v_log_f32_e32 v138, v138
	v_log_f32_e32 v139, v139
	v_log_f32_e32 v140, v140
	v_log_f32_e32 v141, v141
	v_max_f32_e32 v165, 0x0da24260, v165
	v_max_f32_e32 v166, 0x0da24260, v166
	v_max_f32_e32 v167, 0x0da24260, v167
	v_max_f32_e32 v168, 0x0da24260, v168
	v_rcp_f32_e32 v165, v165
	v_rcp_f32_e32 v166, v166
	v_rcp_f32_e32 v167, v167
	v_rcp_f32_e32 v168, v168
	v_mul_f32_e32 v165, v134, v165
	v_mul_f32_e32 v166, v135, v166
	v_mul_f32_e32 v167, v136, v167
	v_mul_f32_e32 v168, v137, v168
	v_mul_f32_e32 v138, v138, v165
	v_mul_f32_e32 v139, v139, v166
	v_mul_f32_e32 v140, v140, v167
	v_mul_f32_e32 v141, v141, v168
	v_fmamk_f32 v169, v138, 0x3f317218, v169
	v_fmamk_f32 v170, v139, 0x3f317218, v170
	v_fmamk_f32 v171, v140, 0x3f317218, v171
	v_fmamk_f32 v172, v141, 0x3f317218, v172
	v_sub_f32_e32 v169, -0.5, v169
	v_sub_f32_e32 v170, -0.5, v170
	v_sub_f32_e32 v171, -0.5, v171
	v_sub_f32_e32 v172, -0.5, v172
	v_mul_f32_e32 v169, 0x3fb8aa3b, v169
	v_mul_f32_e32 v170, 0x3fb8aa3b, v170
	v_mul_f32_e32 v171, 0x3fb8aa3b, v171
	v_mul_f32_e32 v172, 0x3fb8aa3b, v172
	v_exp_f32_e32 v169, v169
	v_exp_f32_e32 v170, v170
	v_exp_f32_e32 v171, v171
	v_exp_f32_e32 v172, v172
	v_mul_f32_e32 v169, 0xbfb8aa3b, v169
	v_mul_f32_e32 v170, 0xbfb8aa3b, v170
	v_mul_f32_e32 v171, 0xbfb8aa3b, v171
	v_mul_f32_e32 v172, 0xbfb8aa3b, v172
	v_exp_f32_e32 v230, v169
	v_exp_f32_e32 v231, v170
	v_exp_f32_e32 v232, v171
	v_exp_f32_e32 v233, v172
	global_store_dwordx4 v[184:185], v[230:233], off offset:64
	v_add_f32_e32 v226, v86, v218
	v_add_f32_e32 v227, v87, v219
	v_add_f32_e32 v228, v88, v220
	v_add_f32_e32 v229, v89, v221
	v_mul_f32_e64 v134, |v226|, s86
	v_mul_f32_e64 v135, |v227|, s86
	v_mul_f32_e64 v136, |v228|, s86
	v_mul_f32_e64 v137, |v229|, s86
	v_exp_f32_e32 v134, v134
	v_exp_f32_e32 v135, v135
	v_exp_f32_e32 v136, v136
	v_exp_f32_e32 v137, v137
	v_max_f32_e64 v169, -v226, 0
	v_max_f32_e64 v170, -v227, 0
	v_max_f32_e64 v171, -v228, 0
	v_max_f32_e64 v172, -v229, 0
	v_add_f32_e32 v138, 1.0, v134
	v_add_f32_e32 v139, 1.0, v135
	v_add_f32_e32 v140, 1.0, v136
	v_add_f32_e32 v141, 1.0, v137
	v_add_f32_e32 v165, -1.0, v138
	v_add_f32_e32 v166, -1.0, v139
	v_add_f32_e32 v167, -1.0, v140
	v_add_f32_e32 v168, -1.0, v141
	v_log_f32_e32 v138, v138
	v_log_f32_e32 v139, v139
	v_log_f32_e32 v140, v140
	v_log_f32_e32 v141, v141
	v_max_f32_e32 v165, 0x0da24260, v165
	v_max_f32_e32 v166, 0x0da24260, v166
	v_max_f32_e32 v167, 0x0da24260, v167
	v_max_f32_e32 v168, 0x0da24260, v168
	v_rcp_f32_e32 v165, v165
	v_rcp_f32_e32 v166, v166
	v_rcp_f32_e32 v167, v167
	v_rcp_f32_e32 v168, v168
	v_mul_f32_e32 v165, v134, v165
	v_mul_f32_e32 v166, v135, v166
	v_mul_f32_e32 v167, v136, v167
	v_mul_f32_e32 v168, v137, v168
	v_mul_f32_e32 v138, v138, v165
	v_mul_f32_e32 v139, v139, v166
	v_mul_f32_e32 v140, v140, v167
	v_mul_f32_e32 v141, v141, v168
	v_fmamk_f32 v169, v138, 0x3f317218, v169
	v_fmamk_f32 v170, v139, 0x3f317218, v170
	v_fmamk_f32 v171, v140, 0x3f317218, v171
	v_fmamk_f32 v172, v141, 0x3f317218, v172
	v_sub_f32_e32 v169, -0.5, v169
	v_sub_f32_e32 v170, -0.5, v170
	v_sub_f32_e32 v171, -0.5, v171
	v_sub_f32_e32 v172, -0.5, v172
	v_mul_f32_e32 v169, 0x3fb8aa3b, v169
	v_mul_f32_e32 v170, 0x3fb8aa3b, v170
	v_mul_f32_e32 v171, 0x3fb8aa3b, v171
	v_mul_f32_e32 v172, 0x3fb8aa3b, v172
	v_exp_f32_e32 v169, v169
	v_exp_f32_e32 v170, v170
	v_exp_f32_e32 v171, v171
	v_exp_f32_e32 v172, v172
	v_mul_f32_e32 v169, 0xbfb8aa3b, v169
	v_mul_f32_e32 v170, 0xbfb8aa3b, v170
	v_mul_f32_e32 v171, 0xbfb8aa3b, v171
	v_mul_f32_e32 v172, 0xbfb8aa3b, v172
	v_exp_f32_e32 v226, v169
	v_exp_f32_e32 v227, v170
	v_exp_f32_e32 v228, v171
	v_exp_f32_e32 v229, v172
	global_store_dwordx4 v[184:185], v[226:229], off offset:512
	v_add_f32_e32 v230, v82, v222
	v_add_f32_e32 v231, v83, v223
	v_add_f32_e32 v232, v84, v224
	v_add_f32_e32 v233, v85, v225
	v_mul_f32_e64 v134, |v230|, s86
	v_mul_f32_e64 v135, |v231|, s86
	v_mul_f32_e64 v136, |v232|, s86
	v_mul_f32_e64 v137, |v233|, s86
	v_exp_f32_e32 v134, v134
	v_exp_f32_e32 v135, v135
	v_exp_f32_e32 v136, v136
	v_exp_f32_e32 v137, v137
	v_max_f32_e64 v169, -v230, 0
	v_max_f32_e64 v170, -v231, 0
	v_max_f32_e64 v171, -v232, 0
	v_max_f32_e64 v172, -v233, 0
	v_add_f32_e32 v138, 1.0, v134
	v_add_f32_e32 v139, 1.0, v135
	v_add_f32_e32 v140, 1.0, v136
	v_add_f32_e32 v141, 1.0, v137
	v_add_f32_e32 v165, -1.0, v138
	v_add_f32_e32 v166, -1.0, v139
	v_add_f32_e32 v167, -1.0, v140
	v_add_f32_e32 v168, -1.0, v141
	v_log_f32_e32 v138, v138
	v_log_f32_e32 v139, v139
	v_log_f32_e32 v140, v140
	v_log_f32_e32 v141, v141
	v_max_f32_e32 v165, 0x0da24260, v165
	v_max_f32_e32 v166, 0x0da24260, v166
	v_max_f32_e32 v167, 0x0da24260, v167
	v_max_f32_e32 v168, 0x0da24260, v168
	v_rcp_f32_e32 v165, v165
	v_rcp_f32_e32 v166, v166
	v_rcp_f32_e32 v167, v167
	v_rcp_f32_e32 v168, v168
	v_mul_f32_e32 v165, v134, v165
	v_mul_f32_e32 v166, v135, v166
	v_mul_f32_e32 v167, v136, v167
	v_mul_f32_e32 v168, v137, v168
	v_mul_f32_e32 v138, v138, v165
	v_mul_f32_e32 v139, v139, v166
	v_mul_f32_e32 v140, v140, v167
	v_mul_f32_e32 v141, v141, v168
	v_fmamk_f32 v169, v138, 0x3f317218, v169
	v_fmamk_f32 v170, v139, 0x3f317218, v170
	v_fmamk_f32 v171, v140, 0x3f317218, v171
	v_fmamk_f32 v172, v141, 0x3f317218, v172
	v_sub_f32_e32 v169, -0.5, v169
	v_sub_f32_e32 v170, -0.5, v170
	v_sub_f32_e32 v171, -0.5, v171
	v_sub_f32_e32 v172, -0.5, v172
	v_mul_f32_e32 v169, 0x3fb8aa3b, v169
	v_mul_f32_e32 v170, 0x3fb8aa3b, v170
	v_mul_f32_e32 v171, 0x3fb8aa3b, v171
	v_mul_f32_e32 v172, 0x3fb8aa3b, v172
	v_exp_f32_e32 v169, v169
	v_exp_f32_e32 v170, v170
	v_exp_f32_e32 v171, v171
	v_exp_f32_e32 v172, v172
	v_mul_f32_e32 v169, 0xbfb8aa3b, v169
	v_mul_f32_e32 v170, 0xbfb8aa3b, v170
	v_mul_f32_e32 v171, 0xbfb8aa3b, v171
	v_mul_f32_e32 v172, 0xbfb8aa3b, v172
	v_exp_f32_e32 v230, v169
	v_exp_f32_e32 v231, v170
	v_exp_f32_e32 v232, v171
	v_exp_f32_e32 v233, v172
	global_store_dwordx4 v[184:185], v[230:233], off offset:576
	v_add_f32_e32 v226, v78, v210
	v_add_f32_e32 v227, v79, v211
	v_add_f32_e32 v228, v80, v212
	v_add_f32_e32 v229, v81, v213
	v_mul_f32_e64 v134, |v226|, s86
	v_mul_f32_e64 v135, |v227|, s86
	v_mul_f32_e64 v136, |v228|, s86
	v_mul_f32_e64 v137, |v229|, s86
	v_exp_f32_e32 v134, v134
	v_exp_f32_e32 v135, v135
	v_exp_f32_e32 v136, v136
	v_exp_f32_e32 v137, v137
	v_max_f32_e64 v169, -v226, 0
	v_max_f32_e64 v170, -v227, 0
	v_max_f32_e64 v171, -v228, 0
	v_max_f32_e64 v172, -v229, 0
	v_add_f32_e32 v138, 1.0, v134
	v_add_f32_e32 v139, 1.0, v135
	v_add_f32_e32 v140, 1.0, v136
	v_add_f32_e32 v141, 1.0, v137
	v_add_f32_e32 v165, -1.0, v138
	v_add_f32_e32 v166, -1.0, v139
	v_add_f32_e32 v167, -1.0, v140
	v_add_f32_e32 v168, -1.0, v141
	v_log_f32_e32 v138, v138
	v_log_f32_e32 v139, v139
	v_log_f32_e32 v140, v140
	v_log_f32_e32 v141, v141
	v_max_f32_e32 v165, 0x0da24260, v165
	v_max_f32_e32 v166, 0x0da24260, v166
	v_max_f32_e32 v167, 0x0da24260, v167
	v_max_f32_e32 v168, 0x0da24260, v168
	v_rcp_f32_e32 v165, v165
	v_rcp_f32_e32 v166, v166
	v_rcp_f32_e32 v167, v167
	v_rcp_f32_e32 v168, v168
	v_mul_f32_e32 v165, v134, v165
	v_mul_f32_e32 v166, v135, v166
	v_mul_f32_e32 v167, v136, v167
	v_mul_f32_e32 v168, v137, v168
	v_mul_f32_e32 v138, v138, v165
	v_mul_f32_e32 v139, v139, v166
	v_mul_f32_e32 v140, v140, v167
	v_mul_f32_e32 v141, v141, v168
	v_fmamk_f32 v169, v138, 0x3f317218, v169
	v_fmamk_f32 v170, v139, 0x3f317218, v170
	v_fmamk_f32 v171, v140, 0x3f317218, v171
	v_fmamk_f32 v172, v141, 0x3f317218, v172
	v_sub_f32_e32 v169, -0.5, v169
	v_sub_f32_e32 v170, -0.5, v170
	v_sub_f32_e32 v171, -0.5, v171
	v_sub_f32_e32 v172, -0.5, v172
	v_mul_f32_e32 v169, 0x3fb8aa3b, v169
	v_mul_f32_e32 v170, 0x3fb8aa3b, v170
	v_mul_f32_e32 v171, 0x3fb8aa3b, v171
	v_mul_f32_e32 v172, 0x3fb8aa3b, v172
	v_exp_f32_e32 v169, v169
	v_exp_f32_e32 v170, v170
	v_exp_f32_e32 v171, v171
	v_exp_f32_e32 v172, v172
	v_mul_f32_e32 v169, 0xbfb8aa3b, v169
	v_mul_f32_e32 v170, 0xbfb8aa3b, v170
	v_mul_f32_e32 v171, 0xbfb8aa3b, v171
	v_mul_f32_e32 v172, 0xbfb8aa3b, v172
	v_exp_f32_e32 v226, v169
	v_exp_f32_e32 v227, v170
	v_exp_f32_e32 v228, v171
	v_exp_f32_e32 v229, v172
	global_store_dwordx4 v[186:187], v[226:229], off
	v_add_f32_e32 v230, v74, v214
	v_add_f32_e32 v231, v75, v215
	v_add_f32_e32 v232, v76, v216
	v_add_f32_e32 v233, v77, v217
	v_mul_f32_e64 v134, |v230|, s86
	v_mul_f32_e64 v135, |v231|, s86
	v_mul_f32_e64 v136, |v232|, s86
	v_mul_f32_e64 v137, |v233|, s86
	v_exp_f32_e32 v134, v134
	v_exp_f32_e32 v135, v135
	v_exp_f32_e32 v136, v136
	v_exp_f32_e32 v137, v137
	v_max_f32_e64 v169, -v230, 0
	v_max_f32_e64 v170, -v231, 0
	v_max_f32_e64 v171, -v232, 0
	v_max_f32_e64 v172, -v233, 0
	v_add_f32_e32 v138, 1.0, v134
	v_add_f32_e32 v139, 1.0, v135
	v_add_f32_e32 v140, 1.0, v136
	v_add_f32_e32 v141, 1.0, v137
	v_add_f32_e32 v165, -1.0, v138
	v_add_f32_e32 v166, -1.0, v139
	v_add_f32_e32 v167, -1.0, v140
	v_add_f32_e32 v168, -1.0, v141
	v_log_f32_e32 v138, v138
	v_log_f32_e32 v139, v139
	v_log_f32_e32 v140, v140
	v_log_f32_e32 v141, v141
	v_max_f32_e32 v165, 0x0da24260, v165
	v_max_f32_e32 v166, 0x0da24260, v166
	v_max_f32_e32 v167, 0x0da24260, v167
	v_max_f32_e32 v168, 0x0da24260, v168
	v_rcp_f32_e32 v165, v165
	v_rcp_f32_e32 v166, v166
	v_rcp_f32_e32 v167, v167
	v_rcp_f32_e32 v168, v168
	v_mul_f32_e32 v165, v134, v165
	v_mul_f32_e32 v166, v135, v166
	v_mul_f32_e32 v167, v136, v167
	v_mul_f32_e32 v168, v137, v168
	v_mul_f32_e32 v138, v138, v165
	v_mul_f32_e32 v139, v139, v166
	v_mul_f32_e32 v140, v140, v167
	v_mul_f32_e32 v141, v141, v168
	v_fmamk_f32 v169, v138, 0x3f317218, v169
	v_fmamk_f32 v170, v139, 0x3f317218, v170
	v_fmamk_f32 v171, v140, 0x3f317218, v171
	v_fmamk_f32 v172, v141, 0x3f317218, v172
	v_sub_f32_e32 v169, -0.5, v169
	v_sub_f32_e32 v170, -0.5, v170
	v_sub_f32_e32 v171, -0.5, v171
	v_sub_f32_e32 v172, -0.5, v172
	v_mul_f32_e32 v169, 0x3fb8aa3b, v169
	v_mul_f32_e32 v170, 0x3fb8aa3b, v170
	v_mul_f32_e32 v171, 0x3fb8aa3b, v171
	v_mul_f32_e32 v172, 0x3fb8aa3b, v172
	v_exp_f32_e32 v169, v169
	v_exp_f32_e32 v170, v170
	v_exp_f32_e32 v171, v171
	v_exp_f32_e32 v172, v172
	v_mul_f32_e32 v169, 0xbfb8aa3b, v169
	v_mul_f32_e32 v170, 0xbfb8aa3b, v170
	v_mul_f32_e32 v171, 0xbfb8aa3b, v171
	v_mul_f32_e32 v172, 0xbfb8aa3b, v172
	v_exp_f32_e32 v230, v169
	v_exp_f32_e32 v231, v170
	v_exp_f32_e32 v232, v171
	v_exp_f32_e32 v233, v172
	global_store_dwordx4 v[186:187], v[230:233], off offset:64
	v_add_f32_e32 v226, v70, v218
	v_add_f32_e32 v227, v71, v219
	v_add_f32_e32 v228, v72, v220
	v_add_f32_e32 v229, v73, v221
	v_mul_f32_e64 v134, |v226|, s86
	v_mul_f32_e64 v135, |v227|, s86
	v_mul_f32_e64 v136, |v228|, s86
	v_mul_f32_e64 v137, |v229|, s86
	v_exp_f32_e32 v134, v134
	v_exp_f32_e32 v135, v135
	v_exp_f32_e32 v136, v136
	v_exp_f32_e32 v137, v137
	v_max_f32_e64 v169, -v226, 0
	v_max_f32_e64 v170, -v227, 0
	v_max_f32_e64 v171, -v228, 0
	v_max_f32_e64 v172, -v229, 0
	v_add_f32_e32 v138, 1.0, v134
	v_add_f32_e32 v139, 1.0, v135
	v_add_f32_e32 v140, 1.0, v136
	v_add_f32_e32 v141, 1.0, v137
	v_add_f32_e32 v165, -1.0, v138
	v_add_f32_e32 v166, -1.0, v139
	v_add_f32_e32 v167, -1.0, v140
	v_add_f32_e32 v168, -1.0, v141
	v_log_f32_e32 v138, v138
	v_log_f32_e32 v139, v139
	v_log_f32_e32 v140, v140
	v_log_f32_e32 v141, v141
	v_max_f32_e32 v165, 0x0da24260, v165
	v_max_f32_e32 v166, 0x0da24260, v166
	v_max_f32_e32 v167, 0x0da24260, v167
	v_max_f32_e32 v168, 0x0da24260, v168
	v_rcp_f32_e32 v165, v165
	v_rcp_f32_e32 v166, v166
	v_rcp_f32_e32 v167, v167
	v_rcp_f32_e32 v168, v168
	v_mul_f32_e32 v165, v134, v165
	v_mul_f32_e32 v166, v135, v166
	v_mul_f32_e32 v167, v136, v167
	v_mul_f32_e32 v168, v137, v168
	v_mul_f32_e32 v138, v138, v165
	v_mul_f32_e32 v139, v139, v166
	v_mul_f32_e32 v140, v140, v167
	v_mul_f32_e32 v141, v141, v168
	v_fmamk_f32 v169, v138, 0x3f317218, v169
	v_fmamk_f32 v170, v139, 0x3f317218, v170
	v_fmamk_f32 v171, v140, 0x3f317218, v171
	v_fmamk_f32 v172, v141, 0x3f317218, v172
	v_sub_f32_e32 v169, -0.5, v169
	v_sub_f32_e32 v170, -0.5, v170
	v_sub_f32_e32 v171, -0.5, v171
	v_sub_f32_e32 v172, -0.5, v172
	v_mul_f32_e32 v169, 0x3fb8aa3b, v169
	v_mul_f32_e32 v170, 0x3fb8aa3b, v170
	v_mul_f32_e32 v171, 0x3fb8aa3b, v171
	v_mul_f32_e32 v172, 0x3fb8aa3b, v172
	v_exp_f32_e32 v169, v169
	v_exp_f32_e32 v170, v170
	v_exp_f32_e32 v171, v171
	v_exp_f32_e32 v172, v172
	v_mul_f32_e32 v169, 0xbfb8aa3b, v169
	v_mul_f32_e32 v170, 0xbfb8aa3b, v170
	v_mul_f32_e32 v171, 0xbfb8aa3b, v171
	v_mul_f32_e32 v172, 0xbfb8aa3b, v172
	v_exp_f32_e32 v226, v169
	v_exp_f32_e32 v227, v170
	v_exp_f32_e32 v228, v171
	v_exp_f32_e32 v229, v172
	global_store_dwordx4 v[186:187], v[226:229], off offset:512
	v_add_f32_e32 v230, v66, v222
	v_add_f32_e32 v231, v67, v223
	v_add_f32_e32 v232, v68, v224
	v_add_f32_e32 v233, v69, v225
	v_mul_f32_e64 v134, |v230|, s86
	v_mul_f32_e64 v135, |v231|, s86
	v_mul_f32_e64 v136, |v232|, s86
	v_mul_f32_e64 v137, |v233|, s86
	v_exp_f32_e32 v134, v134
	v_exp_f32_e32 v135, v135
	v_exp_f32_e32 v136, v136
	v_exp_f32_e32 v137, v137
	v_max_f32_e64 v169, -v230, 0
	v_max_f32_e64 v170, -v231, 0
	v_max_f32_e64 v171, -v232, 0
	v_max_f32_e64 v172, -v233, 0
	v_add_f32_e32 v138, 1.0, v134
	v_add_f32_e32 v139, 1.0, v135
	v_add_f32_e32 v140, 1.0, v136
	v_add_f32_e32 v141, 1.0, v137
	v_add_f32_e32 v165, -1.0, v138
	v_add_f32_e32 v166, -1.0, v139
	v_add_f32_e32 v167, -1.0, v140
	v_add_f32_e32 v168, -1.0, v141
	v_log_f32_e32 v138, v138
	v_log_f32_e32 v139, v139
	v_log_f32_e32 v140, v140
	v_log_f32_e32 v141, v141
	v_max_f32_e32 v165, 0x0da24260, v165
	v_max_f32_e32 v166, 0x0da24260, v166
	v_max_f32_e32 v167, 0x0da24260, v167
	v_max_f32_e32 v168, 0x0da24260, v168
	v_rcp_f32_e32 v165, v165
	v_rcp_f32_e32 v166, v166
	v_rcp_f32_e32 v167, v167
	v_rcp_f32_e32 v168, v168
	v_mul_f32_e32 v165, v134, v165
	v_mul_f32_e32 v166, v135, v166
	v_mul_f32_e32 v167, v136, v167
	v_mul_f32_e32 v168, v137, v168
	v_mul_f32_e32 v138, v138, v165
	v_mul_f32_e32 v139, v139, v166
	v_mul_f32_e32 v140, v140, v167
	v_mul_f32_e32 v141, v141, v168
	v_fmamk_f32 v169, v138, 0x3f317218, v169
	v_fmamk_f32 v170, v139, 0x3f317218, v170
	v_fmamk_f32 v171, v140, 0x3f317218, v171
	v_fmamk_f32 v172, v141, 0x3f317218, v172
	v_sub_f32_e32 v169, -0.5, v169
	v_sub_f32_e32 v170, -0.5, v170
	v_sub_f32_e32 v171, -0.5, v171
	v_sub_f32_e32 v172, -0.5, v172
	v_mul_f32_e32 v169, 0x3fb8aa3b, v169
	v_mul_f32_e32 v170, 0x3fb8aa3b, v170
	v_mul_f32_e32 v171, 0x3fb8aa3b, v171
	v_mul_f32_e32 v172, 0x3fb8aa3b, v172
	v_exp_f32_e32 v169, v169
	v_exp_f32_e32 v170, v170
	v_exp_f32_e32 v171, v171
	v_exp_f32_e32 v172, v172
	v_mul_f32_e32 v169, 0xbfb8aa3b, v169
	v_mul_f32_e32 v170, 0xbfb8aa3b, v170
	v_mul_f32_e32 v171, 0xbfb8aa3b, v171
	v_mul_f32_e32 v172, 0xbfb8aa3b, v172
	v_exp_f32_e32 v230, v169
	v_exp_f32_e32 v231, v170
	v_exp_f32_e32 v232, v171
	v_exp_f32_e32 v233, v172
	global_store_dwordx4 v[186:187], v[230:233], off offset:576
	v_add_f32_e32 v226, v62, v210
	v_add_f32_e32 v227, v63, v211
	v_add_f32_e32 v228, v64, v212
	v_add_f32_e32 v229, v65, v213
	v_mul_f32_e64 v134, |v226|, s86
	v_mul_f32_e64 v135, |v227|, s86
	v_mul_f32_e64 v136, |v228|, s86
	v_mul_f32_e64 v137, |v229|, s86
	v_exp_f32_e32 v134, v134
	v_exp_f32_e32 v135, v135
	v_exp_f32_e32 v136, v136
	v_exp_f32_e32 v137, v137
	v_max_f32_e64 v169, -v226, 0
	v_max_f32_e64 v170, -v227, 0
	v_max_f32_e64 v171, -v228, 0
	v_max_f32_e64 v172, -v229, 0
	v_add_f32_e32 v138, 1.0, v134
	v_add_f32_e32 v139, 1.0, v135
	v_add_f32_e32 v140, 1.0, v136
	v_add_f32_e32 v141, 1.0, v137
	v_add_f32_e32 v165, -1.0, v138
	v_add_f32_e32 v166, -1.0, v139
	v_add_f32_e32 v167, -1.0, v140
	v_add_f32_e32 v168, -1.0, v141
	v_log_f32_e32 v138, v138
	v_log_f32_e32 v139, v139
	v_log_f32_e32 v140, v140
	v_log_f32_e32 v141, v141
	v_max_f32_e32 v165, 0x0da24260, v165
	v_max_f32_e32 v166, 0x0da24260, v166
	v_max_f32_e32 v167, 0x0da24260, v167
	v_max_f32_e32 v168, 0x0da24260, v168
	v_rcp_f32_e32 v165, v165
	v_rcp_f32_e32 v166, v166
	v_rcp_f32_e32 v167, v167
	v_rcp_f32_e32 v168, v168
	v_mul_f32_e32 v165, v134, v165
	v_mul_f32_e32 v166, v135, v166
	v_mul_f32_e32 v167, v136, v167
	v_mul_f32_e32 v168, v137, v168
	v_mul_f32_e32 v138, v138, v165
	v_mul_f32_e32 v139, v139, v166
	v_mul_f32_e32 v140, v140, v167
	v_mul_f32_e32 v141, v141, v168
	v_fmamk_f32 v169, v138, 0x3f317218, v169
	v_fmamk_f32 v170, v139, 0x3f317218, v170
	v_fmamk_f32 v171, v140, 0x3f317218, v171
	v_fmamk_f32 v172, v141, 0x3f317218, v172
	v_sub_f32_e32 v169, -0.5, v169
	v_sub_f32_e32 v170, -0.5, v170
	v_sub_f32_e32 v171, -0.5, v171
	v_sub_f32_e32 v172, -0.5, v172
	v_mul_f32_e32 v169, 0x3fb8aa3b, v169
	v_mul_f32_e32 v170, 0x3fb8aa3b, v170
	v_mul_f32_e32 v171, 0x3fb8aa3b, v171
	v_mul_f32_e32 v172, 0x3fb8aa3b, v172
	v_exp_f32_e32 v169, v169
	v_exp_f32_e32 v170, v170
	v_exp_f32_e32 v171, v171
	v_exp_f32_e32 v172, v172
	v_mul_f32_e32 v169, 0xbfb8aa3b, v169
	v_mul_f32_e32 v170, 0xbfb8aa3b, v170
	v_mul_f32_e32 v171, 0xbfb8aa3b, v171
	v_mul_f32_e32 v172, 0xbfb8aa3b, v172
	v_exp_f32_e32 v226, v169
	v_exp_f32_e32 v227, v170
	v_exp_f32_e32 v228, v171
	v_exp_f32_e32 v229, v172
	global_store_dwordx4 v[188:189], v[226:229], off
	v_add_f32_e32 v230, v58, v214
	v_add_f32_e32 v231, v59, v215
	v_add_f32_e32 v232, v60, v216
	v_add_f32_e32 v233, v61, v217
	v_mul_f32_e64 v134, |v230|, s86
	v_mul_f32_e64 v135, |v231|, s86
	v_mul_f32_e64 v136, |v232|, s86
	v_mul_f32_e64 v137, |v233|, s86
	v_exp_f32_e32 v134, v134
	v_exp_f32_e32 v135, v135
	v_exp_f32_e32 v136, v136
	v_exp_f32_e32 v137, v137
	v_max_f32_e64 v169, -v230, 0
	v_max_f32_e64 v170, -v231, 0
	v_max_f32_e64 v171, -v232, 0
	v_max_f32_e64 v172, -v233, 0
	v_add_f32_e32 v138, 1.0, v134
	v_add_f32_e32 v139, 1.0, v135
	v_add_f32_e32 v140, 1.0, v136
	v_add_f32_e32 v141, 1.0, v137
	v_add_f32_e32 v165, -1.0, v138
	v_add_f32_e32 v166, -1.0, v139
	v_add_f32_e32 v167, -1.0, v140
	v_add_f32_e32 v168, -1.0, v141
	v_log_f32_e32 v138, v138
	v_log_f32_e32 v139, v139
	v_log_f32_e32 v140, v140
	v_log_f32_e32 v141, v141
	v_max_f32_e32 v165, 0x0da24260, v165
	v_max_f32_e32 v166, 0x0da24260, v166
	v_max_f32_e32 v167, 0x0da24260, v167
	v_max_f32_e32 v168, 0x0da24260, v168
	v_rcp_f32_e32 v165, v165
	v_rcp_f32_e32 v166, v166
	v_rcp_f32_e32 v167, v167
	v_rcp_f32_e32 v168, v168
	v_mul_f32_e32 v165, v134, v165
	v_mul_f32_e32 v166, v135, v166
	v_mul_f32_e32 v167, v136, v167
	v_mul_f32_e32 v168, v137, v168
	v_mul_f32_e32 v138, v138, v165
	v_mul_f32_e32 v139, v139, v166
	v_mul_f32_e32 v140, v140, v167
	v_mul_f32_e32 v141, v141, v168
	v_fmamk_f32 v169, v138, 0x3f317218, v169
	v_fmamk_f32 v170, v139, 0x3f317218, v170
	v_fmamk_f32 v171, v140, 0x3f317218, v171
	v_fmamk_f32 v172, v141, 0x3f317218, v172
	v_sub_f32_e32 v169, -0.5, v169
	v_sub_f32_e32 v170, -0.5, v170
	v_sub_f32_e32 v171, -0.5, v171
	v_sub_f32_e32 v172, -0.5, v172
	v_mul_f32_e32 v169, 0x3fb8aa3b, v169
	v_mul_f32_e32 v170, 0x3fb8aa3b, v170
	v_mul_f32_e32 v171, 0x3fb8aa3b, v171
	v_mul_f32_e32 v172, 0x3fb8aa3b, v172
	v_exp_f32_e32 v169, v169
	v_exp_f32_e32 v170, v170
	v_exp_f32_e32 v171, v171
	v_exp_f32_e32 v172, v172
	v_mul_f32_e32 v169, 0xbfb8aa3b, v169
	v_mul_f32_e32 v170, 0xbfb8aa3b, v170
	v_mul_f32_e32 v171, 0xbfb8aa3b, v171
	v_mul_f32_e32 v172, 0xbfb8aa3b, v172
	v_exp_f32_e32 v230, v169
	v_exp_f32_e32 v231, v170
	v_exp_f32_e32 v232, v171
	v_exp_f32_e32 v233, v172
	global_store_dwordx4 v[188:189], v[230:233], off offset:64
	v_add_f32_e32 v226, v54, v218
	v_add_f32_e32 v227, v55, v219
	v_add_f32_e32 v228, v56, v220
	v_add_f32_e32 v229, v57, v221
	v_mul_f32_e64 v134, |v226|, s86
	v_mul_f32_e64 v135, |v227|, s86
	v_mul_f32_e64 v136, |v228|, s86
	v_mul_f32_e64 v137, |v229|, s86
	v_exp_f32_e32 v134, v134
	v_exp_f32_e32 v135, v135
	v_exp_f32_e32 v136, v136
	v_exp_f32_e32 v137, v137
	v_max_f32_e64 v169, -v226, 0
	v_max_f32_e64 v170, -v227, 0
	v_max_f32_e64 v171, -v228, 0
	v_max_f32_e64 v172, -v229, 0
	v_add_f32_e32 v138, 1.0, v134
	v_add_f32_e32 v139, 1.0, v135
	v_add_f32_e32 v140, 1.0, v136
	v_add_f32_e32 v141, 1.0, v137
	v_add_f32_e32 v165, -1.0, v138
	v_add_f32_e32 v166, -1.0, v139
	v_add_f32_e32 v167, -1.0, v140
	v_add_f32_e32 v168, -1.0, v141
	v_log_f32_e32 v138, v138
	v_log_f32_e32 v139, v139
	v_log_f32_e32 v140, v140
	v_log_f32_e32 v141, v141
	v_max_f32_e32 v165, 0x0da24260, v165
	v_max_f32_e32 v166, 0x0da24260, v166
	v_max_f32_e32 v167, 0x0da24260, v167
	v_max_f32_e32 v168, 0x0da24260, v168
	v_rcp_f32_e32 v165, v165
	v_rcp_f32_e32 v166, v166
	v_rcp_f32_e32 v167, v167
	v_rcp_f32_e32 v168, v168
	v_mul_f32_e32 v165, v134, v165
	v_mul_f32_e32 v166, v135, v166
	v_mul_f32_e32 v167, v136, v167
	v_mul_f32_e32 v168, v137, v168
	v_mul_f32_e32 v138, v138, v165
	v_mul_f32_e32 v139, v139, v166
	v_mul_f32_e32 v140, v140, v167
	v_mul_f32_e32 v141, v141, v168
	v_fmamk_f32 v169, v138, 0x3f317218, v169
	v_fmamk_f32 v170, v139, 0x3f317218, v170
	v_fmamk_f32 v171, v140, 0x3f317218, v171
	v_fmamk_f32 v172, v141, 0x3f317218, v172
	v_sub_f32_e32 v169, -0.5, v169
	v_sub_f32_e32 v170, -0.5, v170
	v_sub_f32_e32 v171, -0.5, v171
	v_sub_f32_e32 v172, -0.5, v172
	v_mul_f32_e32 v169, 0x3fb8aa3b, v169
	v_mul_f32_e32 v170, 0x3fb8aa3b, v170
	v_mul_f32_e32 v171, 0x3fb8aa3b, v171
	v_mul_f32_e32 v172, 0x3fb8aa3b, v172
	v_exp_f32_e32 v169, v169
	v_exp_f32_e32 v170, v170
	v_exp_f32_e32 v171, v171
	v_exp_f32_e32 v172, v172
	v_mul_f32_e32 v169, 0xbfb8aa3b, v169
	v_mul_f32_e32 v170, 0xbfb8aa3b, v170
	v_mul_f32_e32 v171, 0xbfb8aa3b, v171
	v_mul_f32_e32 v172, 0xbfb8aa3b, v172
	v_exp_f32_e32 v226, v169
	v_exp_f32_e32 v227, v170
	v_exp_f32_e32 v228, v171
	v_exp_f32_e32 v229, v172
	global_store_dwordx4 v[188:189], v[226:229], off offset:512
	v_add_f32_e32 v230, v50, v222
	v_add_f32_e32 v231, v51, v223
	v_add_f32_e32 v232, v52, v224
	v_add_f32_e32 v233, v53, v225
	v_mul_f32_e64 v134, |v230|, s86
	v_mul_f32_e64 v135, |v231|, s86
	v_mul_f32_e64 v136, |v232|, s86
	v_mul_f32_e64 v137, |v233|, s86
	v_exp_f32_e32 v134, v134
	v_exp_f32_e32 v135, v135
	v_exp_f32_e32 v136, v136
	v_exp_f32_e32 v137, v137
	v_max_f32_e64 v169, -v230, 0
	v_max_f32_e64 v170, -v231, 0
	v_max_f32_e64 v171, -v232, 0
	v_max_f32_e64 v172, -v233, 0
	v_add_f32_e32 v138, 1.0, v134
	v_add_f32_e32 v139, 1.0, v135
	v_add_f32_e32 v140, 1.0, v136
	v_add_f32_e32 v141, 1.0, v137
	v_add_f32_e32 v165, -1.0, v138
	v_add_f32_e32 v166, -1.0, v139
	v_add_f32_e32 v167, -1.0, v140
	v_add_f32_e32 v168, -1.0, v141
	v_log_f32_e32 v138, v138
	v_log_f32_e32 v139, v139
	v_log_f32_e32 v140, v140
	v_log_f32_e32 v141, v141
	v_max_f32_e32 v165, 0x0da24260, v165
	v_max_f32_e32 v166, 0x0da24260, v166
	v_max_f32_e32 v167, 0x0da24260, v167
	v_max_f32_e32 v168, 0x0da24260, v168
	v_rcp_f32_e32 v165, v165
	v_rcp_f32_e32 v166, v166
	v_rcp_f32_e32 v167, v167
	v_rcp_f32_e32 v168, v168
	v_mul_f32_e32 v165, v134, v165
	v_mul_f32_e32 v166, v135, v166
	v_mul_f32_e32 v167, v136, v167
	v_mul_f32_e32 v168, v137, v168
	v_mul_f32_e32 v138, v138, v165
	v_mul_f32_e32 v139, v139, v166
	v_mul_f32_e32 v140, v140, v167
	v_mul_f32_e32 v141, v141, v168
	v_fmamk_f32 v169, v138, 0x3f317218, v169
	v_fmamk_f32 v170, v139, 0x3f317218, v170
	v_fmamk_f32 v171, v140, 0x3f317218, v171
	v_fmamk_f32 v172, v141, 0x3f317218, v172
	v_sub_f32_e32 v169, -0.5, v169
	v_sub_f32_e32 v170, -0.5, v170
	v_sub_f32_e32 v171, -0.5, v171
	v_sub_f32_e32 v172, -0.5, v172
	v_mul_f32_e32 v169, 0x3fb8aa3b, v169
	v_mul_f32_e32 v170, 0x3fb8aa3b, v170
	v_mul_f32_e32 v171, 0x3fb8aa3b, v171
	v_mul_f32_e32 v172, 0x3fb8aa3b, v172
	v_exp_f32_e32 v169, v169
	v_exp_f32_e32 v170, v170
	v_exp_f32_e32 v171, v171
	v_exp_f32_e32 v172, v172
	v_mul_f32_e32 v169, 0xbfb8aa3b, v169
	v_mul_f32_e32 v170, 0xbfb8aa3b, v170
	v_mul_f32_e32 v171, 0xbfb8aa3b, v171
	v_mul_f32_e32 v172, 0xbfb8aa3b, v172
	v_exp_f32_e32 v230, v169
	v_exp_f32_e32 v231, v170
	v_exp_f32_e32 v232, v171
	v_exp_f32_e32 v233, v172
	global_store_dwordx4 v[188:189], v[230:233], off offset:576
	v_add_f32_e32 v226, v46, v210
	v_add_f32_e32 v227, v47, v211
	v_add_f32_e32 v228, v48, v212
	v_add_f32_e32 v229, v49, v213
	v_mul_f32_e64 v134, |v226|, s86
	v_mul_f32_e64 v135, |v227|, s86
	v_mul_f32_e64 v136, |v228|, s86
	v_mul_f32_e64 v137, |v229|, s86
	v_exp_f32_e32 v134, v134
	v_exp_f32_e32 v135, v135
	v_exp_f32_e32 v136, v136
	v_exp_f32_e32 v137, v137
	v_max_f32_e64 v169, -v226, 0
	v_max_f32_e64 v170, -v227, 0
	v_max_f32_e64 v171, -v228, 0
	v_max_f32_e64 v172, -v229, 0
	v_add_f32_e32 v138, 1.0, v134
	v_add_f32_e32 v139, 1.0, v135
	v_add_f32_e32 v140, 1.0, v136
	v_add_f32_e32 v141, 1.0, v137
	v_add_f32_e32 v165, -1.0, v138
	v_add_f32_e32 v166, -1.0, v139
	v_add_f32_e32 v167, -1.0, v140
	v_add_f32_e32 v168, -1.0, v141
	v_log_f32_e32 v138, v138
	v_log_f32_e32 v139, v139
	v_log_f32_e32 v140, v140
	v_log_f32_e32 v141, v141
	v_max_f32_e32 v165, 0x0da24260, v165
	v_max_f32_e32 v166, 0x0da24260, v166
	v_max_f32_e32 v167, 0x0da24260, v167
	v_max_f32_e32 v168, 0x0da24260, v168
	v_rcp_f32_e32 v165, v165
	v_rcp_f32_e32 v166, v166
	v_rcp_f32_e32 v167, v167
	v_rcp_f32_e32 v168, v168
	v_mul_f32_e32 v165, v134, v165
	v_mul_f32_e32 v166, v135, v166
	v_mul_f32_e32 v167, v136, v167
	v_mul_f32_e32 v168, v137, v168
	v_mul_f32_e32 v138, v138, v165
	v_mul_f32_e32 v139, v139, v166
	v_mul_f32_e32 v140, v140, v167
	v_mul_f32_e32 v141, v141, v168
	v_fmamk_f32 v169, v138, 0x3f317218, v169
	v_fmamk_f32 v170, v139, 0x3f317218, v170
	v_fmamk_f32 v171, v140, 0x3f317218, v171
	v_fmamk_f32 v172, v141, 0x3f317218, v172
	v_sub_f32_e32 v169, -0.5, v169
	v_sub_f32_e32 v170, -0.5, v170
	v_sub_f32_e32 v171, -0.5, v171
	v_sub_f32_e32 v172, -0.5, v172
	v_mul_f32_e32 v169, 0x3fb8aa3b, v169
	v_mul_f32_e32 v170, 0x3fb8aa3b, v170
	v_mul_f32_e32 v171, 0x3fb8aa3b, v171
	v_mul_f32_e32 v172, 0x3fb8aa3b, v172
	v_exp_f32_e32 v169, v169
	v_exp_f32_e32 v170, v170
	v_exp_f32_e32 v171, v171
	v_exp_f32_e32 v172, v172
	v_mul_f32_e32 v169, 0xbfb8aa3b, v169
	v_mul_f32_e32 v170, 0xbfb8aa3b, v170
	v_mul_f32_e32 v171, 0xbfb8aa3b, v171
	v_mul_f32_e32 v172, 0xbfb8aa3b, v172
	v_exp_f32_e32 v226, v169
	v_exp_f32_e32 v227, v170
	v_exp_f32_e32 v228, v171
	v_exp_f32_e32 v229, v172
	global_store_dwordx4 v[190:191], v[226:229], off
	v_add_f32_e32 v230, v42, v214
	v_add_f32_e32 v231, v43, v215
	v_add_f32_e32 v232, v44, v216
	v_add_f32_e32 v233, v45, v217
	v_mul_f32_e64 v134, |v230|, s86
	v_mul_f32_e64 v135, |v231|, s86
	v_mul_f32_e64 v136, |v232|, s86
	v_mul_f32_e64 v137, |v233|, s86
	v_exp_f32_e32 v134, v134
	v_exp_f32_e32 v135, v135
	v_exp_f32_e32 v136, v136
	v_exp_f32_e32 v137, v137
	v_max_f32_e64 v169, -v230, 0
	v_max_f32_e64 v170, -v231, 0
	v_max_f32_e64 v171, -v232, 0
	v_max_f32_e64 v172, -v233, 0
	v_add_f32_e32 v138, 1.0, v134
	v_add_f32_e32 v139, 1.0, v135
	v_add_f32_e32 v140, 1.0, v136
	v_add_f32_e32 v141, 1.0, v137
	v_add_f32_e32 v165, -1.0, v138
	v_add_f32_e32 v166, -1.0, v139
	v_add_f32_e32 v167, -1.0, v140
	v_add_f32_e32 v168, -1.0, v141
	v_log_f32_e32 v138, v138
	v_log_f32_e32 v139, v139
	v_log_f32_e32 v140, v140
	v_log_f32_e32 v141, v141
	v_max_f32_e32 v165, 0x0da24260, v165
	v_max_f32_e32 v166, 0x0da24260, v166
	v_max_f32_e32 v167, 0x0da24260, v167
	v_max_f32_e32 v168, 0x0da24260, v168
	v_rcp_f32_e32 v165, v165
	v_rcp_f32_e32 v166, v166
	v_rcp_f32_e32 v167, v167
	v_rcp_f32_e32 v168, v168
	v_mul_f32_e32 v165, v134, v165
	v_mul_f32_e32 v166, v135, v166
	v_mul_f32_e32 v167, v136, v167
	v_mul_f32_e32 v168, v137, v168
	v_mul_f32_e32 v138, v138, v165
	v_mul_f32_e32 v139, v139, v166
	v_mul_f32_e32 v140, v140, v167
	v_mul_f32_e32 v141, v141, v168
	v_fmamk_f32 v169, v138, 0x3f317218, v169
	v_fmamk_f32 v170, v139, 0x3f317218, v170
	v_fmamk_f32 v171, v140, 0x3f317218, v171
	v_fmamk_f32 v172, v141, 0x3f317218, v172
	v_sub_f32_e32 v169, -0.5, v169
	v_sub_f32_e32 v170, -0.5, v170
	v_sub_f32_e32 v171, -0.5, v171
	v_sub_f32_e32 v172, -0.5, v172
	v_mul_f32_e32 v169, 0x3fb8aa3b, v169
	v_mul_f32_e32 v170, 0x3fb8aa3b, v170
	v_mul_f32_e32 v171, 0x3fb8aa3b, v171
	v_mul_f32_e32 v172, 0x3fb8aa3b, v172
	v_exp_f32_e32 v169, v169
	v_exp_f32_e32 v170, v170
	v_exp_f32_e32 v171, v171
	v_exp_f32_e32 v172, v172
	v_mul_f32_e32 v169, 0xbfb8aa3b, v169
	v_mul_f32_e32 v170, 0xbfb8aa3b, v170
	v_mul_f32_e32 v171, 0xbfb8aa3b, v171
	v_mul_f32_e32 v172, 0xbfb8aa3b, v172
	v_exp_f32_e32 v230, v169
	v_exp_f32_e32 v231, v170
	v_exp_f32_e32 v232, v171
	v_exp_f32_e32 v233, v172
	global_store_dwordx4 v[190:191], v[230:233], off offset:64
	v_add_f32_e32 v226, v38, v218
	v_add_f32_e32 v227, v39, v219
	v_add_f32_e32 v228, v40, v220
	v_add_f32_e32 v229, v41, v221
	v_mul_f32_e64 v134, |v226|, s86
	v_mul_f32_e64 v135, |v227|, s86
	v_mul_f32_e64 v136, |v228|, s86
	v_mul_f32_e64 v137, |v229|, s86
	v_exp_f32_e32 v134, v134
	v_exp_f32_e32 v135, v135
	v_exp_f32_e32 v136, v136
	v_exp_f32_e32 v137, v137
	v_max_f32_e64 v169, -v226, 0
	v_max_f32_e64 v170, -v227, 0
	v_max_f32_e64 v171, -v228, 0
	v_max_f32_e64 v172, -v229, 0
	v_add_f32_e32 v138, 1.0, v134
	v_add_f32_e32 v139, 1.0, v135
	v_add_f32_e32 v140, 1.0, v136
	v_add_f32_e32 v141, 1.0, v137
	v_add_f32_e32 v165, -1.0, v138
	v_add_f32_e32 v166, -1.0, v139
	v_add_f32_e32 v167, -1.0, v140
	v_add_f32_e32 v168, -1.0, v141
	v_log_f32_e32 v138, v138
	v_log_f32_e32 v139, v139
	v_log_f32_e32 v140, v140
	v_log_f32_e32 v141, v141
	v_max_f32_e32 v165, 0x0da24260, v165
	v_max_f32_e32 v166, 0x0da24260, v166
	v_max_f32_e32 v167, 0x0da24260, v167
	v_max_f32_e32 v168, 0x0da24260, v168
	v_rcp_f32_e32 v165, v165
	v_rcp_f32_e32 v166, v166
	v_rcp_f32_e32 v167, v167
	v_rcp_f32_e32 v168, v168
	v_mul_f32_e32 v165, v134, v165
	v_mul_f32_e32 v166, v135, v166
	v_mul_f32_e32 v167, v136, v167
	v_mul_f32_e32 v168, v137, v168
	v_mul_f32_e32 v138, v138, v165
	v_mul_f32_e32 v139, v139, v166
	v_mul_f32_e32 v140, v140, v167
	v_mul_f32_e32 v141, v141, v168
	v_fmamk_f32 v169, v138, 0x3f317218, v169
	v_fmamk_f32 v170, v139, 0x3f317218, v170
	v_fmamk_f32 v171, v140, 0x3f317218, v171
	v_fmamk_f32 v172, v141, 0x3f317218, v172
	v_sub_f32_e32 v169, -0.5, v169
	v_sub_f32_e32 v170, -0.5, v170
	v_sub_f32_e32 v171, -0.5, v171
	v_sub_f32_e32 v172, -0.5, v172
	v_mul_f32_e32 v169, 0x3fb8aa3b, v169
	v_mul_f32_e32 v170, 0x3fb8aa3b, v170
	v_mul_f32_e32 v171, 0x3fb8aa3b, v171
	v_mul_f32_e32 v172, 0x3fb8aa3b, v172
	v_exp_f32_e32 v169, v169
	v_exp_f32_e32 v170, v170
	v_exp_f32_e32 v171, v171
	v_exp_f32_e32 v172, v172
	v_mul_f32_e32 v169, 0xbfb8aa3b, v169
	v_mul_f32_e32 v170, 0xbfb8aa3b, v170
	v_mul_f32_e32 v171, 0xbfb8aa3b, v171
	v_mul_f32_e32 v172, 0xbfb8aa3b, v172
	v_exp_f32_e32 v226, v169
	v_exp_f32_e32 v227, v170
	v_exp_f32_e32 v228, v171
	v_exp_f32_e32 v229, v172
	global_store_dwordx4 v[190:191], v[226:229], off offset:512
	v_add_f32_e32 v230, v34, v222
	v_add_f32_e32 v231, v35, v223
	v_add_f32_e32 v232, v36, v224
	v_add_f32_e32 v233, v37, v225
	v_mul_f32_e64 v134, |v230|, s86
	v_mul_f32_e64 v135, |v231|, s86
	v_mul_f32_e64 v136, |v232|, s86
	v_mul_f32_e64 v137, |v233|, s86
	v_exp_f32_e32 v134, v134
	v_exp_f32_e32 v135, v135
	v_exp_f32_e32 v136, v136
	v_exp_f32_e32 v137, v137
	v_max_f32_e64 v169, -v230, 0
	v_max_f32_e64 v170, -v231, 0
	v_max_f32_e64 v171, -v232, 0
	v_max_f32_e64 v172, -v233, 0
	v_add_f32_e32 v138, 1.0, v134
	v_add_f32_e32 v139, 1.0, v135
	v_add_f32_e32 v140, 1.0, v136
	v_add_f32_e32 v141, 1.0, v137
	v_add_f32_e32 v165, -1.0, v138
	v_add_f32_e32 v166, -1.0, v139
	v_add_f32_e32 v167, -1.0, v140
	v_add_f32_e32 v168, -1.0, v141
	v_log_f32_e32 v138, v138
	v_log_f32_e32 v139, v139
	v_log_f32_e32 v140, v140
	v_log_f32_e32 v141, v141
	v_max_f32_e32 v165, 0x0da24260, v165
	v_max_f32_e32 v166, 0x0da24260, v166
	v_max_f32_e32 v167, 0x0da24260, v167
	v_max_f32_e32 v168, 0x0da24260, v168
	v_rcp_f32_e32 v165, v165
	v_rcp_f32_e32 v166, v166
	v_rcp_f32_e32 v167, v167
	v_rcp_f32_e32 v168, v168
	v_mul_f32_e32 v165, v134, v165
	v_mul_f32_e32 v166, v135, v166
	v_mul_f32_e32 v167, v136, v167
	v_mul_f32_e32 v168, v137, v168
	v_mul_f32_e32 v138, v138, v165
	v_mul_f32_e32 v139, v139, v166
	v_mul_f32_e32 v140, v140, v167
	v_mul_f32_e32 v141, v141, v168
	v_fmamk_f32 v169, v138, 0x3f317218, v169
	v_fmamk_f32 v170, v139, 0x3f317218, v170
	v_fmamk_f32 v171, v140, 0x3f317218, v171
	v_fmamk_f32 v172, v141, 0x3f317218, v172
	v_sub_f32_e32 v169, -0.5, v169
	v_sub_f32_e32 v170, -0.5, v170
	v_sub_f32_e32 v171, -0.5, v171
	v_sub_f32_e32 v172, -0.5, v172
	v_mul_f32_e32 v169, 0x3fb8aa3b, v169
	v_mul_f32_e32 v170, 0x3fb8aa3b, v170
	v_mul_f32_e32 v171, 0x3fb8aa3b, v171
	v_mul_f32_e32 v172, 0x3fb8aa3b, v172
	v_exp_f32_e32 v169, v169
	v_exp_f32_e32 v170, v170
	v_exp_f32_e32 v171, v171
	v_exp_f32_e32 v172, v172
	v_mul_f32_e32 v169, 0xbfb8aa3b, v169
	v_mul_f32_e32 v170, 0xbfb8aa3b, v170
	v_mul_f32_e32 v171, 0xbfb8aa3b, v171
	v_mul_f32_e32 v172, 0xbfb8aa3b, v172
	v_exp_f32_e32 v230, v169
	v_exp_f32_e32 v231, v170
	v_exp_f32_e32 v232, v171
	v_exp_f32_e32 v233, v172
	global_store_dwordx4 v[190:191], v[230:233], off offset:576
	v_add_f32_e32 v226, v30, v210
	v_add_f32_e32 v227, v31, v211
	v_add_f32_e32 v228, v32, v212
	v_add_f32_e32 v229, v33, v213
	v_mul_f32_e64 v134, |v226|, s86
	v_mul_f32_e64 v135, |v227|, s86
	v_mul_f32_e64 v136, |v228|, s86
	v_mul_f32_e64 v137, |v229|, s86
	v_exp_f32_e32 v134, v134
	v_exp_f32_e32 v135, v135
	v_exp_f32_e32 v136, v136
	v_exp_f32_e32 v137, v137
	v_max_f32_e64 v169, -v226, 0
	v_max_f32_e64 v170, -v227, 0
	v_max_f32_e64 v171, -v228, 0
	v_max_f32_e64 v172, -v229, 0
	v_add_f32_e32 v138, 1.0, v134
	v_add_f32_e32 v139, 1.0, v135
	v_add_f32_e32 v140, 1.0, v136
	v_add_f32_e32 v141, 1.0, v137
	v_add_f32_e32 v165, -1.0, v138
	v_add_f32_e32 v166, -1.0, v139
	v_add_f32_e32 v167, -1.0, v140
	v_add_f32_e32 v168, -1.0, v141
	v_log_f32_e32 v138, v138
	v_log_f32_e32 v139, v139
	v_log_f32_e32 v140, v140
	v_log_f32_e32 v141, v141
	v_max_f32_e32 v165, 0x0da24260, v165
	v_max_f32_e32 v166, 0x0da24260, v166
	v_max_f32_e32 v167, 0x0da24260, v167
	v_max_f32_e32 v168, 0x0da24260, v168
	v_rcp_f32_e32 v165, v165
	v_rcp_f32_e32 v166, v166
	v_rcp_f32_e32 v167, v167
	v_rcp_f32_e32 v168, v168
	v_mul_f32_e32 v165, v134, v165
	v_mul_f32_e32 v166, v135, v166
	v_mul_f32_e32 v167, v136, v167
	v_mul_f32_e32 v168, v137, v168
	v_mul_f32_e32 v138, v138, v165
	v_mul_f32_e32 v139, v139, v166
	v_mul_f32_e32 v140, v140, v167
	v_mul_f32_e32 v141, v141, v168
	v_fmamk_f32 v169, v138, 0x3f317218, v169
	v_fmamk_f32 v170, v139, 0x3f317218, v170
	v_fmamk_f32 v171, v140, 0x3f317218, v171
	v_fmamk_f32 v172, v141, 0x3f317218, v172
	v_sub_f32_e32 v169, -0.5, v169
	v_sub_f32_e32 v170, -0.5, v170
	v_sub_f32_e32 v171, -0.5, v171
	v_sub_f32_e32 v172, -0.5, v172
	v_mul_f32_e32 v169, 0x3fb8aa3b, v169
	v_mul_f32_e32 v170, 0x3fb8aa3b, v170
	v_mul_f32_e32 v171, 0x3fb8aa3b, v171
	v_mul_f32_e32 v172, 0x3fb8aa3b, v172
	v_exp_f32_e32 v169, v169
	v_exp_f32_e32 v170, v170
	v_exp_f32_e32 v171, v171
	v_exp_f32_e32 v172, v172
	v_mul_f32_e32 v169, 0xbfb8aa3b, v169
	v_mul_f32_e32 v170, 0xbfb8aa3b, v170
	v_mul_f32_e32 v171, 0xbfb8aa3b, v171
	v_mul_f32_e32 v172, 0xbfb8aa3b, v172
	v_exp_f32_e32 v226, v169
	v_exp_f32_e32 v227, v170
	v_exp_f32_e32 v228, v171
	v_exp_f32_e32 v229, v172
	global_store_dwordx4 v[192:193], v[226:229], off
	v_add_f32_e32 v230, v24, v214
	v_add_f32_e32 v231, v25, v215
	v_add_f32_e32 v232, v26, v216
	v_add_f32_e32 v233, v27, v217
	v_mul_f32_e64 v134, |v230|, s86
	v_mul_f32_e64 v135, |v231|, s86
	v_mul_f32_e64 v136, |v232|, s86
	v_mul_f32_e64 v137, |v233|, s86
	v_exp_f32_e32 v134, v134
	v_exp_f32_e32 v135, v135
	v_exp_f32_e32 v136, v136
	v_exp_f32_e32 v137, v137
	v_max_f32_e64 v169, -v230, 0
	v_max_f32_e64 v170, -v231, 0
	v_max_f32_e64 v171, -v232, 0
	v_max_f32_e64 v172, -v233, 0
	v_add_f32_e32 v138, 1.0, v134
	v_add_f32_e32 v139, 1.0, v135
	v_add_f32_e32 v140, 1.0, v136
	v_add_f32_e32 v141, 1.0, v137
	v_add_f32_e32 v165, -1.0, v138
	v_add_f32_e32 v166, -1.0, v139
	v_add_f32_e32 v167, -1.0, v140
	v_add_f32_e32 v168, -1.0, v141
	v_log_f32_e32 v138, v138
	v_log_f32_e32 v139, v139
	v_log_f32_e32 v140, v140
	v_log_f32_e32 v141, v141
	v_max_f32_e32 v165, 0x0da24260, v165
	v_max_f32_e32 v166, 0x0da24260, v166
	v_max_f32_e32 v167, 0x0da24260, v167
	v_max_f32_e32 v168, 0x0da24260, v168
	v_rcp_f32_e32 v165, v165
	v_rcp_f32_e32 v166, v166
	v_rcp_f32_e32 v167, v167
	v_rcp_f32_e32 v168, v168
	v_mul_f32_e32 v165, v134, v165
	v_mul_f32_e32 v166, v135, v166
	v_mul_f32_e32 v167, v136, v167
	v_mul_f32_e32 v168, v137, v168
	v_mul_f32_e32 v138, v138, v165
	v_mul_f32_e32 v139, v139, v166
	v_mul_f32_e32 v140, v140, v167
	v_mul_f32_e32 v141, v141, v168
	v_fmamk_f32 v169, v138, 0x3f317218, v169
	v_fmamk_f32 v170, v139, 0x3f317218, v170
	v_fmamk_f32 v171, v140, 0x3f317218, v171
	v_fmamk_f32 v172, v141, 0x3f317218, v172
	v_sub_f32_e32 v169, -0.5, v169
	v_sub_f32_e32 v170, -0.5, v170
	v_sub_f32_e32 v171, -0.5, v171
	v_sub_f32_e32 v172, -0.5, v172
	v_mul_f32_e32 v169, 0x3fb8aa3b, v169
	v_mul_f32_e32 v170, 0x3fb8aa3b, v170
	v_mul_f32_e32 v171, 0x3fb8aa3b, v171
	v_mul_f32_e32 v172, 0x3fb8aa3b, v172
	v_exp_f32_e32 v169, v169
	v_exp_f32_e32 v170, v170
	v_exp_f32_e32 v171, v171
	v_exp_f32_e32 v172, v172
	v_mul_f32_e32 v169, 0xbfb8aa3b, v169
	v_mul_f32_e32 v170, 0xbfb8aa3b, v170
	v_mul_f32_e32 v171, 0xbfb8aa3b, v171
	v_mul_f32_e32 v172, 0xbfb8aa3b, v172
	v_exp_f32_e32 v230, v169
	v_exp_f32_e32 v231, v170
	v_exp_f32_e32 v232, v171
	v_exp_f32_e32 v233, v172
	global_store_dwordx4 v[192:193], v[230:233], off offset:64
	v_add_f32_e32 v226, v20, v218
	v_add_f32_e32 v227, v21, v219
	v_add_f32_e32 v228, v22, v220
	v_add_f32_e32 v229, v23, v221
	v_mul_f32_e64 v134, |v226|, s86
	v_mul_f32_e64 v135, |v227|, s86
	v_mul_f32_e64 v136, |v228|, s86
	v_mul_f32_e64 v137, |v229|, s86
	v_exp_f32_e32 v134, v134
	v_exp_f32_e32 v135, v135
	v_exp_f32_e32 v136, v136
	v_exp_f32_e32 v137, v137
	v_max_f32_e64 v169, -v226, 0
	v_max_f32_e64 v170, -v227, 0
	v_max_f32_e64 v171, -v228, 0
	v_max_f32_e64 v172, -v229, 0
	v_add_f32_e32 v138, 1.0, v134
	v_add_f32_e32 v139, 1.0, v135
	v_add_f32_e32 v140, 1.0, v136
	v_add_f32_e32 v141, 1.0, v137
	v_add_f32_e32 v165, -1.0, v138
	v_add_f32_e32 v166, -1.0, v139
	v_add_f32_e32 v167, -1.0, v140
	v_add_f32_e32 v168, -1.0, v141
	v_log_f32_e32 v138, v138
	v_log_f32_e32 v139, v139
	v_log_f32_e32 v140, v140
	v_log_f32_e32 v141, v141
	v_max_f32_e32 v165, 0x0da24260, v165
	v_max_f32_e32 v166, 0x0da24260, v166
	v_max_f32_e32 v167, 0x0da24260, v167
	v_max_f32_e32 v168, 0x0da24260, v168
	v_rcp_f32_e32 v165, v165
	v_rcp_f32_e32 v166, v166
	v_rcp_f32_e32 v167, v167
	v_rcp_f32_e32 v168, v168
	v_mul_f32_e32 v165, v134, v165
	v_mul_f32_e32 v166, v135, v166
	v_mul_f32_e32 v167, v136, v167
	v_mul_f32_e32 v168, v137, v168
	v_mul_f32_e32 v138, v138, v165
	v_mul_f32_e32 v139, v139, v166
	v_mul_f32_e32 v140, v140, v167
	v_mul_f32_e32 v141, v141, v168
	v_fmamk_f32 v169, v138, 0x3f317218, v169
	v_fmamk_f32 v170, v139, 0x3f317218, v170
	v_fmamk_f32 v171, v140, 0x3f317218, v171
	v_fmamk_f32 v172, v141, 0x3f317218, v172
	v_sub_f32_e32 v169, -0.5, v169
	v_sub_f32_e32 v170, -0.5, v170
	v_sub_f32_e32 v171, -0.5, v171
	v_sub_f32_e32 v172, -0.5, v172
	v_mul_f32_e32 v169, 0x3fb8aa3b, v169
	v_mul_f32_e32 v170, 0x3fb8aa3b, v170
	v_mul_f32_e32 v171, 0x3fb8aa3b, v171
	v_mul_f32_e32 v172, 0x3fb8aa3b, v172
	v_exp_f32_e32 v169, v169
	v_exp_f32_e32 v170, v170
	v_exp_f32_e32 v171, v171
	v_exp_f32_e32 v172, v172
	v_mul_f32_e32 v169, 0xbfb8aa3b, v169
	v_mul_f32_e32 v170, 0xbfb8aa3b, v170
	v_mul_f32_e32 v171, 0xbfb8aa3b, v171
	v_mul_f32_e32 v172, 0xbfb8aa3b, v172
	v_exp_f32_e32 v226, v169
	v_exp_f32_e32 v227, v170
	v_exp_f32_e32 v228, v171
	v_exp_f32_e32 v229, v172
	global_store_dwordx4 v[192:193], v[226:229], off offset:512
	v_add_f32_e32 v230, v16, v222
	v_add_f32_e32 v231, v17, v223
	v_add_f32_e32 v232, v18, v224
	v_add_f32_e32 v233, v19, v225
	v_mul_f32_e64 v134, |v230|, s86
	v_mul_f32_e64 v135, |v231|, s86
	v_mul_f32_e64 v136, |v232|, s86
	v_mul_f32_e64 v137, |v233|, s86
	v_exp_f32_e32 v134, v134
	v_exp_f32_e32 v135, v135
	v_exp_f32_e32 v136, v136
	v_exp_f32_e32 v137, v137
	v_max_f32_e64 v169, -v230, 0
	v_max_f32_e64 v170, -v231, 0
	v_max_f32_e64 v171, -v232, 0
	v_max_f32_e64 v172, -v233, 0
	v_add_f32_e32 v138, 1.0, v134
	v_add_f32_e32 v139, 1.0, v135
	v_add_f32_e32 v140, 1.0, v136
	v_add_f32_e32 v141, 1.0, v137
	v_add_f32_e32 v165, -1.0, v138
	v_add_f32_e32 v166, -1.0, v139
	v_add_f32_e32 v167, -1.0, v140
	v_add_f32_e32 v168, -1.0, v141
	v_log_f32_e32 v138, v138
	v_log_f32_e32 v139, v139
	v_log_f32_e32 v140, v140
	v_log_f32_e32 v141, v141
	v_max_f32_e32 v165, 0x0da24260, v165
	v_max_f32_e32 v166, 0x0da24260, v166
	v_max_f32_e32 v167, 0x0da24260, v167
	v_max_f32_e32 v168, 0x0da24260, v168
	v_rcp_f32_e32 v165, v165
	v_rcp_f32_e32 v166, v166
	v_rcp_f32_e32 v167, v167
	v_rcp_f32_e32 v168, v168
	v_mul_f32_e32 v165, v134, v165
	v_mul_f32_e32 v166, v135, v166
	v_mul_f32_e32 v167, v136, v167
	v_mul_f32_e32 v168, v137, v168
	v_mul_f32_e32 v138, v138, v165
	v_mul_f32_e32 v139, v139, v166
	v_mul_f32_e32 v140, v140, v167
	v_mul_f32_e32 v141, v141, v168
	v_fmamk_f32 v169, v138, 0x3f317218, v169
	v_fmamk_f32 v170, v139, 0x3f317218, v170
	v_fmamk_f32 v171, v140, 0x3f317218, v171
	v_fmamk_f32 v172, v141, 0x3f317218, v172
	v_sub_f32_e32 v169, -0.5, v169
	v_sub_f32_e32 v170, -0.5, v170
	v_sub_f32_e32 v171, -0.5, v171
	v_sub_f32_e32 v172, -0.5, v172
	v_mul_f32_e32 v169, 0x3fb8aa3b, v169
	v_mul_f32_e32 v170, 0x3fb8aa3b, v170
	v_mul_f32_e32 v171, 0x3fb8aa3b, v171
	v_mul_f32_e32 v172, 0x3fb8aa3b, v172
	v_exp_f32_e32 v169, v169
	v_exp_f32_e32 v170, v170
	v_exp_f32_e32 v171, v171
	v_exp_f32_e32 v172, v172
	v_mul_f32_e32 v169, 0xbfb8aa3b, v169
	v_mul_f32_e32 v170, 0xbfb8aa3b, v170
	v_mul_f32_e32 v171, 0xbfb8aa3b, v171
	v_mul_f32_e32 v172, 0xbfb8aa3b, v172
	v_exp_f32_e32 v230, v169
	v_exp_f32_e32 v231, v170
	v_exp_f32_e32 v232, v171
	v_exp_f32_e32 v233, v172
	global_store_dwordx4 v[192:193], v[230:233], off offset:576
	v_add_f32_e32 v226, v12, v210
	v_add_f32_e32 v227, v13, v211
	v_add_f32_e32 v228, v14, v212
	v_add_f32_e32 v229, v15, v213
	v_mul_f32_e64 v134, |v226|, s86
	v_mul_f32_e64 v135, |v227|, s86
	v_mul_f32_e64 v136, |v228|, s86
	v_mul_f32_e64 v137, |v229|, s86
	v_exp_f32_e32 v134, v134
	v_exp_f32_e32 v135, v135
	v_exp_f32_e32 v136, v136
	v_exp_f32_e32 v137, v137
	v_max_f32_e64 v169, -v226, 0
	v_max_f32_e64 v170, -v227, 0
	v_max_f32_e64 v171, -v228, 0
	v_max_f32_e64 v172, -v229, 0
	v_add_f32_e32 v138, 1.0, v134
	v_add_f32_e32 v139, 1.0, v135
	v_add_f32_e32 v140, 1.0, v136
	v_add_f32_e32 v141, 1.0, v137
	v_add_f32_e32 v165, -1.0, v138
	v_add_f32_e32 v166, -1.0, v139
	v_add_f32_e32 v167, -1.0, v140
	v_add_f32_e32 v168, -1.0, v141
	v_log_f32_e32 v138, v138
	v_log_f32_e32 v139, v139
	v_log_f32_e32 v140, v140
	v_log_f32_e32 v141, v141
	v_max_f32_e32 v165, 0x0da24260, v165
	v_max_f32_e32 v166, 0x0da24260, v166
	v_max_f32_e32 v167, 0x0da24260, v167
	v_max_f32_e32 v168, 0x0da24260, v168
	v_rcp_f32_e32 v165, v165
	v_rcp_f32_e32 v166, v166
	v_rcp_f32_e32 v167, v167
	v_rcp_f32_e32 v168, v168
	v_mul_f32_e32 v165, v134, v165
	v_mul_f32_e32 v166, v135, v166
	v_mul_f32_e32 v167, v136, v167
	v_mul_f32_e32 v168, v137, v168
	v_mul_f32_e32 v138, v138, v165
	v_mul_f32_e32 v139, v139, v166
	v_mul_f32_e32 v140, v140, v167
	v_mul_f32_e32 v141, v141, v168
	v_fmamk_f32 v169, v138, 0x3f317218, v169
	v_fmamk_f32 v170, v139, 0x3f317218, v170
	v_fmamk_f32 v171, v140, 0x3f317218, v171
	v_fmamk_f32 v172, v141, 0x3f317218, v172
	v_sub_f32_e32 v169, -0.5, v169
	v_sub_f32_e32 v170, -0.5, v170
	v_sub_f32_e32 v171, -0.5, v171
	v_sub_f32_e32 v172, -0.5, v172
	v_mul_f32_e32 v169, 0x3fb8aa3b, v169
	v_mul_f32_e32 v170, 0x3fb8aa3b, v170
	v_mul_f32_e32 v171, 0x3fb8aa3b, v171
	v_mul_f32_e32 v172, 0x3fb8aa3b, v172
	v_exp_f32_e32 v169, v169
	v_exp_f32_e32 v170, v170
	v_exp_f32_e32 v171, v171
	v_exp_f32_e32 v172, v172
	v_mul_f32_e32 v169, 0xbfb8aa3b, v169
	v_mul_f32_e32 v170, 0xbfb8aa3b, v170
	v_mul_f32_e32 v171, 0xbfb8aa3b, v171
	v_mul_f32_e32 v172, 0xbfb8aa3b, v172
	v_exp_f32_e32 v226, v169
	v_exp_f32_e32 v227, v170
	v_exp_f32_e32 v228, v171
	v_exp_f32_e32 v229, v172
	global_store_dwordx4 v[194:195], v[226:229], off
	v_add_f32_e32 v230, v8, v214
	v_add_f32_e32 v231, v9, v215
	v_add_f32_e32 v232, v10, v216
	v_add_f32_e32 v233, v11, v217
	v_mul_f32_e64 v134, |v230|, s86
	v_mul_f32_e64 v135, |v231|, s86
	v_mul_f32_e64 v136, |v232|, s86
	v_mul_f32_e64 v137, |v233|, s86
	v_exp_f32_e32 v134, v134
	v_exp_f32_e32 v135, v135
	v_exp_f32_e32 v136, v136
	v_exp_f32_e32 v137, v137
	v_max_f32_e64 v169, -v230, 0
	v_max_f32_e64 v170, -v231, 0
	v_max_f32_e64 v171, -v232, 0
	v_max_f32_e64 v172, -v233, 0
	v_add_f32_e32 v138, 1.0, v134
	v_add_f32_e32 v139, 1.0, v135
	v_add_f32_e32 v140, 1.0, v136
	v_add_f32_e32 v141, 1.0, v137
	v_add_f32_e32 v165, -1.0, v138
	v_add_f32_e32 v166, -1.0, v139
	v_add_f32_e32 v167, -1.0, v140
	v_add_f32_e32 v168, -1.0, v141
	v_log_f32_e32 v138, v138
	v_log_f32_e32 v139, v139
	v_log_f32_e32 v140, v140
	v_log_f32_e32 v141, v141
	v_max_f32_e32 v165, 0x0da24260, v165
	v_max_f32_e32 v166, 0x0da24260, v166
	v_max_f32_e32 v167, 0x0da24260, v167
	v_max_f32_e32 v168, 0x0da24260, v168
	v_rcp_f32_e32 v165, v165
	v_rcp_f32_e32 v166, v166
	v_rcp_f32_e32 v167, v167
	v_rcp_f32_e32 v168, v168
	v_mul_f32_e32 v165, v134, v165
	v_mul_f32_e32 v166, v135, v166
	v_mul_f32_e32 v167, v136, v167
	v_mul_f32_e32 v168, v137, v168
	v_mul_f32_e32 v138, v138, v165
	v_mul_f32_e32 v139, v139, v166
	v_mul_f32_e32 v140, v140, v167
	v_mul_f32_e32 v141, v141, v168
	v_fmamk_f32 v169, v138, 0x3f317218, v169
	v_fmamk_f32 v170, v139, 0x3f317218, v170
	v_fmamk_f32 v171, v140, 0x3f317218, v171
	v_fmamk_f32 v172, v141, 0x3f317218, v172
	v_sub_f32_e32 v169, -0.5, v169
	v_sub_f32_e32 v170, -0.5, v170
	v_sub_f32_e32 v171, -0.5, v171
	v_sub_f32_e32 v172, -0.5, v172
	v_mul_f32_e32 v169, 0x3fb8aa3b, v169
	v_mul_f32_e32 v170, 0x3fb8aa3b, v170
	v_mul_f32_e32 v171, 0x3fb8aa3b, v171
	v_mul_f32_e32 v172, 0x3fb8aa3b, v172
	v_exp_f32_e32 v169, v169
	v_exp_f32_e32 v170, v170
	v_exp_f32_e32 v171, v171
	v_exp_f32_e32 v172, v172
	v_mul_f32_e32 v169, 0xbfb8aa3b, v169
	v_mul_f32_e32 v170, 0xbfb8aa3b, v170
	v_mul_f32_e32 v171, 0xbfb8aa3b, v171
	v_mul_f32_e32 v172, 0xbfb8aa3b, v172
	v_exp_f32_e32 v230, v169
	v_exp_f32_e32 v231, v170
	v_exp_f32_e32 v232, v171
	v_exp_f32_e32 v233, v172
	global_store_dwordx4 v[194:195], v[230:233], off offset:64
	v_add_f32_e32 v226, v4, v218
	v_add_f32_e32 v227, v5, v219
	v_add_f32_e32 v228, v6, v220
	v_add_f32_e32 v229, v7, v221
	v_mul_f32_e64 v134, |v226|, s86
	v_mul_f32_e64 v135, |v227|, s86
	v_mul_f32_e64 v136, |v228|, s86
	v_mul_f32_e64 v137, |v229|, s86
	v_exp_f32_e32 v134, v134
	v_exp_f32_e32 v135, v135
	v_exp_f32_e32 v136, v136
	v_exp_f32_e32 v137, v137
	v_max_f32_e64 v169, -v226, 0
	v_max_f32_e64 v170, -v227, 0
	v_max_f32_e64 v171, -v228, 0
	v_max_f32_e64 v172, -v229, 0
	v_add_f32_e32 v138, 1.0, v134
	v_add_f32_e32 v139, 1.0, v135
	v_add_f32_e32 v140, 1.0, v136
	v_add_f32_e32 v141, 1.0, v137
	v_add_f32_e32 v165, -1.0, v138
	v_add_f32_e32 v166, -1.0, v139
	v_add_f32_e32 v167, -1.0, v140
	v_add_f32_e32 v168, -1.0, v141
	v_log_f32_e32 v138, v138
	v_log_f32_e32 v139, v139
	v_log_f32_e32 v140, v140
	v_log_f32_e32 v141, v141
	v_max_f32_e32 v165, 0x0da24260, v165
	v_max_f32_e32 v166, 0x0da24260, v166
	v_max_f32_e32 v167, 0x0da24260, v167
	v_max_f32_e32 v168, 0x0da24260, v168
	v_rcp_f32_e32 v165, v165
	v_rcp_f32_e32 v166, v166
	v_rcp_f32_e32 v167, v167
	v_rcp_f32_e32 v168, v168
	v_mul_f32_e32 v165, v134, v165
	v_mul_f32_e32 v166, v135, v166
	v_mul_f32_e32 v167, v136, v167
	v_mul_f32_e32 v168, v137, v168
	v_mul_f32_e32 v138, v138, v165
	v_mul_f32_e32 v139, v139, v166
	v_mul_f32_e32 v140, v140, v167
	v_mul_f32_e32 v141, v141, v168
	v_fmamk_f32 v169, v138, 0x3f317218, v169
	v_fmamk_f32 v170, v139, 0x3f317218, v170
	v_fmamk_f32 v171, v140, 0x3f317218, v171
	v_fmamk_f32 v172, v141, 0x3f317218, v172
	v_sub_f32_e32 v169, -0.5, v169
	v_sub_f32_e32 v170, -0.5, v170
	v_sub_f32_e32 v171, -0.5, v171
	v_sub_f32_e32 v172, -0.5, v172
	v_mul_f32_e32 v169, 0x3fb8aa3b, v169
	v_mul_f32_e32 v170, 0x3fb8aa3b, v170
	v_mul_f32_e32 v171, 0x3fb8aa3b, v171
	v_mul_f32_e32 v172, 0x3fb8aa3b, v172
	v_exp_f32_e32 v169, v169
	v_exp_f32_e32 v170, v170
	v_exp_f32_e32 v171, v171
	v_exp_f32_e32 v172, v172
	v_mul_f32_e32 v169, 0xbfb8aa3b, v169
	v_mul_f32_e32 v170, 0xbfb8aa3b, v170
	v_mul_f32_e32 v171, 0xbfb8aa3b, v171
	v_mul_f32_e32 v172, 0xbfb8aa3b, v172
	v_exp_f32_e32 v226, v169
	v_exp_f32_e32 v227, v170
	v_exp_f32_e32 v228, v171
	v_exp_f32_e32 v229, v172
	global_store_dwordx4 v[194:195], v[226:229], off offset:512
	v_add_f32_e32 v230, v0, v222
	v_add_f32_e32 v231, v1, v223
	v_add_f32_e32 v232, v2, v224
	v_add_f32_e32 v233, v3, v225
	v_mul_f32_e64 v134, |v230|, s86
	v_mul_f32_e64 v135, |v231|, s86
	v_mul_f32_e64 v136, |v232|, s86
	v_mul_f32_e64 v137, |v233|, s86
	v_exp_f32_e32 v134, v134
	v_exp_f32_e32 v135, v135
	v_exp_f32_e32 v136, v136
	v_exp_f32_e32 v137, v137
	v_max_f32_e64 v169, -v230, 0
	v_max_f32_e64 v170, -v231, 0
	v_max_f32_e64 v171, -v232, 0
	v_max_f32_e64 v172, -v233, 0
	v_add_f32_e32 v138, 1.0, v134
	v_add_f32_e32 v139, 1.0, v135
	v_add_f32_e32 v140, 1.0, v136
	v_add_f32_e32 v141, 1.0, v137
	v_add_f32_e32 v165, -1.0, v138
	v_add_f32_e32 v166, -1.0, v139
	v_add_f32_e32 v167, -1.0, v140
	v_add_f32_e32 v168, -1.0, v141
	v_log_f32_e32 v138, v138
	v_log_f32_e32 v139, v139
	v_log_f32_e32 v140, v140
	v_log_f32_e32 v141, v141
	v_max_f32_e32 v165, 0x0da24260, v165
	v_max_f32_e32 v166, 0x0da24260, v166
	v_max_f32_e32 v167, 0x0da24260, v167
	v_max_f32_e32 v168, 0x0da24260, v168
	v_rcp_f32_e32 v165, v165
	v_rcp_f32_e32 v166, v166
	v_rcp_f32_e32 v167, v167
	v_rcp_f32_e32 v168, v168
	v_mul_f32_e32 v165, v134, v165
	v_mul_f32_e32 v166, v135, v166
	v_mul_f32_e32 v167, v136, v167
	v_mul_f32_e32 v168, v137, v168
	v_mul_f32_e32 v138, v138, v165
	v_mul_f32_e32 v139, v139, v166
	v_mul_f32_e32 v140, v140, v167
	v_mul_f32_e32 v141, v141, v168
	v_fmamk_f32 v169, v138, 0x3f317218, v169
	v_fmamk_f32 v170, v139, 0x3f317218, v170
	v_fmamk_f32 v171, v140, 0x3f317218, v171
	v_fmamk_f32 v172, v141, 0x3f317218, v172
	v_sub_f32_e32 v169, -0.5, v169
	v_sub_f32_e32 v170, -0.5, v170
	v_sub_f32_e32 v171, -0.5, v171
	v_sub_f32_e32 v172, -0.5, v172
	v_mul_f32_e32 v169, 0x3fb8aa3b, v169
	v_mul_f32_e32 v170, 0x3fb8aa3b, v170
	v_mul_f32_e32 v171, 0x3fb8aa3b, v171
	v_mul_f32_e32 v172, 0x3fb8aa3b, v172
	v_exp_f32_e32 v169, v169
	v_exp_f32_e32 v170, v170
	v_exp_f32_e32 v171, v171
	v_exp_f32_e32 v172, v172
	v_mul_f32_e32 v169, 0xbfb8aa3b, v169
	v_mul_f32_e32 v170, 0xbfb8aa3b, v170
	v_mul_f32_e32 v171, 0xbfb8aa3b, v171
	v_mul_f32_e32 v172, 0xbfb8aa3b, v172
	v_exp_f32_e32 v230, v169
	v_exp_f32_e32 v231, v170
	v_exp_f32_e32 v232, v171
	v_exp_f32_e32 v233, v172
	global_store_dwordx4 v[194:195], v[230:233], off offset:576
	s_mov_b64 s[2:3], 0
